# phase-3 scan: non-temporal hint on its read-once state loads (keeps the freshly written entering states cached for phase 4)
# baseline (speedup 1.0000x reference)
.LBB0_571:
	v_readlane_b32 s0, v253, 4
	s_cmp_lt_i32 s0, 4
	s_cbranch_scc1 .LBB0_638
	s_mov_b64 s[6:7], exec
	s_load_dwordx4 s[8:11], s[92:93], 0x110
	v_readfirstlane_b32 s12, v162
	v_and_b32_e32 v1, 0xffff, v162
	s_lshr_b32 s13, s12, 16
	s_and_b32 s14, s12, 0xffff
	s_lshl_b32 s15, s13, 25
	s_waitcnt lgkmcnt(0)
	s_cmp_lt_u32 s14, 0x8000
	s_cbranch_scc0 .Lp3_ssd
	s_add_u32 s16, s8, s15
	s_addc_u32 s17, s9, 0
	s_mov_b64 s[18:19], s[16:17]
	v_lshlrev_b32_e32 v2, 2, v1
	s_lshr_b32 s20, s14, 13
	v_cvt_f32_u32_e32 v3, s20
	v_sub_f32_e32 v3, 0xc0a00000, v3
	v_exp_f32_e32 v3, v3
	s_nop 0
	v_sub_f32_e32 v3, 1.0, v3
	v_log_f32_e32 v3, v3
	s_nop 0
	v_mul_f32_e32 v3, 0x42800000, v3
	v_exp_f32_e32 v3, v3
	s_nop 1
	v_readfirstlane_b32 s21, v3
	v_mov_b32_e32 v4, 0
	v_mov_b32_e32 v5, 0
	global_load_dword v8, v2, s[16:17] nt
	s_add_u32 s16, s16, 0x20000
	s_addc_u32 s17, s17, 0
	global_load_dword v9, v2, s[16:17] nt
	s_add_u32 s16, s16, 0x20000
	s_addc_u32 s17, s17, 0
	global_load_dword v10, v2, s[16:17] nt
	s_add_u32 s16, s16, 0x20000
	s_addc_u32 s17, s17, 0
	global_load_dword v11, v2, s[16:17] nt
	s_add_u32 s16, s16, 0x20000
	s_addc_u32 s17, s17, 0
	global_load_dword v12, v2, s[16:17] nt
	s_add_u32 s16, s16, 0x20000
	s_addc_u32 s17, s17, 0
	global_load_dword v13, v2, s[16:17] nt
	s_add_u32 s16, s16, 0x20000
	s_addc_u32 s17, s17, 0
	global_load_dword v14, v2, s[16:17] nt
	s_add_u32 s16, s16, 0x20000
	s_addc_u32 s17, s17, 0
	global_load_dword v15, v2, s[16:17] nt
	s_add_u32 s16, s16, 0x20000
	s_addc_u32 s17, s17, 0
	global_load_dword v16, v2, s[16:17] nt
	s_add_u32 s16, s16, 0x20000
	s_addc_u32 s17, s17, 0
	global_load_dword v17, v2, s[16:17] nt
	s_add_u32 s16, s16, 0x20000
	s_addc_u32 s17, s17, 0
	global_load_dword v18, v2, s[16:17] nt
	s_add_u32 s16, s16, 0x20000
	s_addc_u32 s17, s17, 0
	global_load_dword v19, v2, s[16:17] nt
	s_add_u32 s16, s16, 0x20000
	s_addc_u32 s17, s17, 0
	global_load_dword v20, v2, s[16:17] nt
	s_add_u32 s16, s16, 0x20000
	s_addc_u32 s17, s17, 0
	global_load_dword v21, v2, s[16:17] nt
	s_add_u32 s16, s16, 0x20000
	s_addc_u32 s17, s17, 0
	global_load_dword v22, v2, s[16:17] nt
	s_add_u32 s16, s16, 0x20000
	s_addc_u32 s17, s17, 0
	global_load_dword v23, v2, s[16:17] nt
	s_add_u32 s16, s16, 0x20000
	s_addc_u32 s17, s17, 0
	global_load_dword v24, v2, s[16:17] nt
	s_add_u32 s16, s16, 0x20000
	s_addc_u32 s17, s17, 0
	global_load_dword v25, v2, s[16:17] nt
	s_add_u32 s16, s16, 0x20000
	s_addc_u32 s17, s17, 0
	global_load_dword v26, v2, s[16:17] nt
	s_add_u32 s16, s16, 0x20000
	s_addc_u32 s17, s17, 0
	global_load_dword v27, v2, s[16:17] nt
	s_add_u32 s16, s16, 0x20000
	s_addc_u32 s17, s17, 0
	global_load_dword v28, v2, s[16:17] nt
	s_add_u32 s16, s16, 0x20000
	s_addc_u32 s17, s17, 0
	global_load_dword v29, v2, s[16:17] nt
	s_add_u32 s16, s16, 0x20000
	s_addc_u32 s17, s17, 0
	global_load_dword v30, v2, s[16:17] nt
	s_add_u32 s16, s16, 0x20000
	s_addc_u32 s17, s17, 0
	global_load_dword v31, v2, s[16:17] nt
	s_add_u32 s16, s16, 0x20000
	s_addc_u32 s17, s17, 0
	global_load_dword v32, v2, s[16:17] nt
	s_add_u32 s16, s16, 0x20000
	s_addc_u32 s17, s17, 0
	global_load_dword v33, v2, s[16:17] nt
	s_add_u32 s16, s16, 0x20000
	s_addc_u32 s17, s17, 0
	global_load_dword v34, v2, s[16:17] nt
	s_add_u32 s16, s16, 0x20000
	s_addc_u32 s17, s17, 0
	global_load_dword v35, v2, s[16:17] nt
	s_add_u32 s16, s16, 0x20000
	s_addc_u32 s17, s17, 0
	global_load_dword v36, v2, s[16:17] nt
	s_add_u32 s16, s16, 0x20000
	s_addc_u32 s17, s17, 0
	global_load_dword v37, v2, s[16:17] nt
	s_add_u32 s16, s16, 0x20000
	s_addc_u32 s17, s17, 0
	global_load_dword v38, v2, s[16:17] nt
	s_add_u32 s16, s16, 0x20000
	s_addc_u32 s17, s17, 0
	global_load_dword v39, v2, s[16:17] nt
	s_add_u32 s16, s16, 0x20000
	s_addc_u32 s17, s17, 0
	s_waitcnt vmcnt(24)
	v_cvt_pk_bf16_f32 v6, v4, v5
	global_store_dword v2, v6, s[18:19]
	s_add_u32 s18, s18, 0x20000
	s_addc_u32 s19, s19, 0
	v_lshlrev_b32_e32 v40, 16, v8
	v_and_b32_e32 v41, 0xffff0000, v8
	v_fma_f32 v4, v4, s21, v40
	v_fma_f32 v5, v5, s21, v41
	v_cvt_pk_bf16_f32 v6, v4, v5
	global_store_dword v2, v6, s[18:19]
	s_add_u32 s18, s18, 0x20000
	s_addc_u32 s19, s19, 0
	v_lshlrev_b32_e32 v40, 16, v9
	v_and_b32_e32 v41, 0xffff0000, v9
	v_fma_f32 v4, v4, s21, v40
	v_fma_f32 v5, v5, s21, v41
	v_cvt_pk_bf16_f32 v6, v4, v5
	global_store_dword v2, v6, s[18:19]
	s_add_u32 s18, s18, 0x20000
	s_addc_u32 s19, s19, 0
	v_lshlrev_b32_e32 v40, 16, v10
	v_and_b32_e32 v41, 0xffff0000, v10
	v_fma_f32 v4, v4, s21, v40
	v_fma_f32 v5, v5, s21, v41
	v_cvt_pk_bf16_f32 v6, v4, v5
	global_store_dword v2, v6, s[18:19]
	s_add_u32 s18, s18, 0x20000
	s_addc_u32 s19, s19, 0
	v_lshlrev_b32_e32 v40, 16, v11
	v_and_b32_e32 v41, 0xffff0000, v11
	v_fma_f32 v4, v4, s21, v40
	v_fma_f32 v5, v5, s21, v41
	v_cvt_pk_bf16_f32 v6, v4, v5
	global_store_dword v2, v6, s[18:19]
	s_add_u32 s18, s18, 0x20000
	s_addc_u32 s19, s19, 0
	v_lshlrev_b32_e32 v40, 16, v12
	v_and_b32_e32 v41, 0xffff0000, v12
	v_fma_f32 v4, v4, s21, v40
	v_fma_f32 v5, v5, s21, v41
	v_cvt_pk_bf16_f32 v6, v4, v5
	global_store_dword v2, v6, s[18:19]
	s_add_u32 s18, s18, 0x20000
	s_addc_u32 s19, s19, 0
	v_lshlrev_b32_e32 v40, 16, v13
	v_and_b32_e32 v41, 0xffff0000, v13
	v_fma_f32 v4, v4, s21, v40
	v_fma_f32 v5, v5, s21, v41
	v_cvt_pk_bf16_f32 v6, v4, v5
	global_store_dword v2, v6, s[18:19]
	s_add_u32 s18, s18, 0x20000
	s_addc_u32 s19, s19, 0
	v_lshlrev_b32_e32 v40, 16, v14
	v_and_b32_e32 v41, 0xffff0000, v14
	v_fma_f32 v4, v4, s21, v40
	v_fma_f32 v5, v5, s21, v41
	v_cvt_pk_bf16_f32 v6, v4, v5
	global_store_dword v2, v6, s[18:19]
	s_add_u32 s18, s18, 0x20000
	s_addc_u32 s19, s19, 0
	v_lshlrev_b32_e32 v40, 16, v15
	v_and_b32_e32 v41, 0xffff0000, v15
	v_fma_f32 v4, v4, s21, v40
	v_fma_f32 v5, v5, s21, v41
	global_load_dword v8, v2, s[16:17] nt
	s_add_u32 s16, s16, 0x20000
	s_addc_u32 s17, s17, 0
	global_load_dword v9, v2, s[16:17] nt
	s_add_u32 s16, s16, 0x20000
	s_addc_u32 s17, s17, 0
	global_load_dword v10, v2, s[16:17] nt
	s_add_u32 s16, s16, 0x20000
	s_addc_u32 s17, s17, 0
	global_load_dword v11, v2, s[16:17] nt
	s_add_u32 s16, s16, 0x20000
	s_addc_u32 s17, s17, 0
	global_load_dword v12, v2, s[16:17] nt
	s_add_u32 s16, s16, 0x20000
	s_addc_u32 s17, s17, 0
	global_load_dword v13, v2, s[16:17] nt
	s_add_u32 s16, s16, 0x20000
	s_addc_u32 s17, s17, 0
	global_load_dword v14, v2, s[16:17] nt
	s_add_u32 s16, s16, 0x20000
	s_addc_u32 s17, s17, 0
	global_load_dword v15, v2, s[16:17] nt
	s_add_u32 s16, s16, 0x20000
	s_addc_u32 s17, s17, 0
	s_waitcnt vmcnt(32)
	v_cvt_pk_bf16_f32 v6, v4, v5
	global_store_dword v2, v6, s[18:19]
	s_add_u32 s18, s18, 0x20000
	s_addc_u32 s19, s19, 0
	v_lshlrev_b32_e32 v40, 16, v16
	v_and_b32_e32 v41, 0xffff0000, v16
	v_fma_f32 v4, v4, s21, v40
	v_fma_f32 v5, v5, s21, v41
	v_cvt_pk_bf16_f32 v6, v4, v5
	global_store_dword v2, v6, s[18:19]
	s_add_u32 s18, s18, 0x20000
	s_addc_u32 s19, s19, 0
	v_lshlrev_b32_e32 v40, 16, v17
	v_and_b32_e32 v41, 0xffff0000, v17
	v_fma_f32 v4, v4, s21, v40
	v_fma_f32 v5, v5, s21, v41
	v_cvt_pk_bf16_f32 v6, v4, v5
	global_store_dword v2, v6, s[18:19]
	s_add_u32 s18, s18, 0x20000
	s_addc_u32 s19, s19, 0
	v_lshlrev_b32_e32 v40, 16, v18
	v_and_b32_e32 v41, 0xffff0000, v18
	v_fma_f32 v4, v4, s21, v40
	v_fma_f32 v5, v5, s21, v41
	v_cvt_pk_bf16_f32 v6, v4, v5
	global_store_dword v2, v6, s[18:19]
	s_add_u32 s18, s18, 0x20000
	s_addc_u32 s19, s19, 0
	v_lshlrev_b32_e32 v40, 16, v19
	v_and_b32_e32 v41, 0xffff0000, v19
	v_fma_f32 v4, v4, s21, v40
	v_fma_f32 v5, v5, s21, v41
	v_cvt_pk_bf16_f32 v6, v4, v5
	global_store_dword v2, v6, s[18:19]
	s_add_u32 s18, s18, 0x20000
	s_addc_u32 s19, s19, 0
	v_lshlrev_b32_e32 v40, 16, v20
	v_and_b32_e32 v41, 0xffff0000, v20
	v_fma_f32 v4, v4, s21, v40
	v_fma_f32 v5, v5, s21, v41
	v_cvt_pk_bf16_f32 v6, v4, v5
	global_store_dword v2, v6, s[18:19]
	s_add_u32 s18, s18, 0x20000
	s_addc_u32 s19, s19, 0
	v_lshlrev_b32_e32 v40, 16, v21
	v_and_b32_e32 v41, 0xffff0000, v21
	v_fma_f32 v4, v4, s21, v40
	v_fma_f32 v5, v5, s21, v41
	v_cvt_pk_bf16_f32 v6, v4, v5
	global_store_dword v2, v6, s[18:19]
	s_add_u32 s18, s18, 0x20000
	s_addc_u32 s19, s19, 0
	v_lshlrev_b32_e32 v40, 16, v22
	v_and_b32_e32 v41, 0xffff0000, v22
	v_fma_f32 v4, v4, s21, v40
	v_fma_f32 v5, v5, s21, v41
	v_cvt_pk_bf16_f32 v6, v4, v5
	global_store_dword v2, v6, s[18:19]
	s_add_u32 s18, s18, 0x20000
	s_addc_u32 s19, s19, 0
	v_lshlrev_b32_e32 v40, 16, v23
	v_and_b32_e32 v41, 0xffff0000, v23
	v_fma_f32 v4, v4, s21, v40
	v_fma_f32 v5, v5, s21, v41
	global_load_dword v16, v2, s[16:17] nt
	s_add_u32 s16, s16, 0x20000
	s_addc_u32 s17, s17, 0
	global_load_dword v17, v2, s[16:17] nt
	s_add_u32 s16, s16, 0x20000
	s_addc_u32 s17, s17, 0
	global_load_dword v18, v2, s[16:17] nt
	s_add_u32 s16, s16, 0x20000
	s_addc_u32 s17, s17, 0
	global_load_dword v19, v2, s[16:17] nt
	s_add_u32 s16, s16, 0x20000
	s_addc_u32 s17, s17, 0
	global_load_dword v20, v2, s[16:17] nt
	s_add_u32 s16, s16, 0x20000
	s_addc_u32 s17, s17, 0
	global_load_dword v21, v2, s[16:17] nt
	s_add_u32 s16, s16, 0x20000
	s_addc_u32 s17, s17, 0
	global_load_dword v22, v2, s[16:17] nt
	s_add_u32 s16, s16, 0x20000
	s_addc_u32 s17, s17, 0
	global_load_dword v23, v2, s[16:17] nt
	s_add_u32 s16, s16, 0x20000
	s_addc_u32 s17, s17, 0
	s_waitcnt vmcnt(40)
	v_cvt_pk_bf16_f32 v6, v4, v5
	global_store_dword v2, v6, s[18:19]
	s_add_u32 s18, s18, 0x20000
	s_addc_u32 s19, s19, 0
	v_lshlrev_b32_e32 v40, 16, v24
	v_and_b32_e32 v41, 0xffff0000, v24
	v_fma_f32 v4, v4, s21, v40
	v_fma_f32 v5, v5, s21, v41
	v_cvt_pk_bf16_f32 v6, v4, v5
	global_store_dword v2, v6, s[18:19]
	s_add_u32 s18, s18, 0x20000
	s_addc_u32 s19, s19, 0
	v_lshlrev_b32_e32 v40, 16, v25
	v_and_b32_e32 v41, 0xffff0000, v25
	v_fma_f32 v4, v4, s21, v40
	v_fma_f32 v5, v5, s21, v41
	v_cvt_pk_bf16_f32 v6, v4, v5
	global_store_dword v2, v6, s[18:19]
	s_add_u32 s18, s18, 0x20000
	s_addc_u32 s19, s19, 0
	v_lshlrev_b32_e32 v40, 16, v26
	v_and_b32_e32 v41, 0xffff0000, v26
	v_fma_f32 v4, v4, s21, v40
	v_fma_f32 v5, v5, s21, v41
	v_cvt_pk_bf16_f32 v6, v4, v5
	global_store_dword v2, v6, s[18:19]
	s_add_u32 s18, s18, 0x20000
	s_addc_u32 s19, s19, 0
	v_lshlrev_b32_e32 v40, 16, v27
	v_and_b32_e32 v41, 0xffff0000, v27
	v_fma_f32 v4, v4, s21, v40
	v_fma_f32 v5, v5, s21, v41
	v_cvt_pk_bf16_f32 v6, v4, v5
	global_store_dword v2, v6, s[18:19]
	s_add_u32 s18, s18, 0x20000
	s_addc_u32 s19, s19, 0
	v_lshlrev_b32_e32 v40, 16, v28
	v_and_b32_e32 v41, 0xffff0000, v28
	v_fma_f32 v4, v4, s21, v40
	v_fma_f32 v5, v5, s21, v41
	v_cvt_pk_bf16_f32 v6, v4, v5
	global_store_dword v2, v6, s[18:19]
	s_add_u32 s18, s18, 0x20000
	s_addc_u32 s19, s19, 0
	v_lshlrev_b32_e32 v40, 16, v29
	v_and_b32_e32 v41, 0xffff0000, v29
	v_fma_f32 v4, v4, s21, v40
	v_fma_f32 v5, v5, s21, v41
	v_cvt_pk_bf16_f32 v6, v4, v5
	global_store_dword v2, v6, s[18:19]
	s_add_u32 s18, s18, 0x20000
	s_addc_u32 s19, s19, 0
	v_lshlrev_b32_e32 v40, 16, v30
	v_and_b32_e32 v41, 0xffff0000, v30
	v_fma_f32 v4, v4, s21, v40
	v_fma_f32 v5, v5, s21, v41
	v_cvt_pk_bf16_f32 v6, v4, v5
	global_store_dword v2, v6, s[18:19]
	s_add_u32 s18, s18, 0x20000
	s_addc_u32 s19, s19, 0
	v_lshlrev_b32_e32 v40, 16, v31
	v_and_b32_e32 v41, 0xffff0000, v31
	v_fma_f32 v4, v4, s21, v40
	v_fma_f32 v5, v5, s21, v41
	global_load_dword v24, v2, s[16:17] nt
	s_add_u32 s16, s16, 0x20000
	s_addc_u32 s17, s17, 0
	global_load_dword v25, v2, s[16:17] nt
	s_add_u32 s16, s16, 0x20000
	s_addc_u32 s17, s17, 0
	global_load_dword v26, v2, s[16:17] nt
	s_add_u32 s16, s16, 0x20000
	s_addc_u32 s17, s17, 0
	global_load_dword v27, v2, s[16:17] nt
	s_add_u32 s16, s16, 0x20000
	s_addc_u32 s17, s17, 0
	global_load_dword v28, v2, s[16:17] nt
	s_add_u32 s16, s16, 0x20000
	s_addc_u32 s17, s17, 0
	global_load_dword v29, v2, s[16:17] nt
	s_add_u32 s16, s16, 0x20000
	s_addc_u32 s17, s17, 0
	global_load_dword v30, v2, s[16:17] nt
	s_add_u32 s16, s16, 0x20000
	s_addc_u32 s17, s17, 0
	global_load_dword v31, v2, s[16:17] nt
	s_add_u32 s16, s16, 0x20000
	s_addc_u32 s17, s17, 0
	s_waitcnt vmcnt(48)
	v_cvt_pk_bf16_f32 v6, v4, v5
	global_store_dword v2, v6, s[18:19]
	s_add_u32 s18, s18, 0x20000
	s_addc_u32 s19, s19, 0
	v_lshlrev_b32_e32 v40, 16, v32
	v_and_b32_e32 v41, 0xffff0000, v32
	v_fma_f32 v4, v4, s21, v40
	v_fma_f32 v5, v5, s21, v41
	v_cvt_pk_bf16_f32 v6, v4, v5
	global_store_dword v2, v6, s[18:19]
	s_add_u32 s18, s18, 0x20000
	s_addc_u32 s19, s19, 0
	v_lshlrev_b32_e32 v40, 16, v33
	v_and_b32_e32 v41, 0xffff0000, v33
	v_fma_f32 v4, v4, s21, v40
	v_fma_f32 v5, v5, s21, v41
	v_cvt_pk_bf16_f32 v6, v4, v5
	global_store_dword v2, v6, s[18:19]
	s_add_u32 s18, s18, 0x20000
	s_addc_u32 s19, s19, 0
	v_lshlrev_b32_e32 v40, 16, v34
	v_and_b32_e32 v41, 0xffff0000, v34
	v_fma_f32 v4, v4, s21, v40
	v_fma_f32 v5, v5, s21, v41
	v_cvt_pk_bf16_f32 v6, v4, v5
	global_store_dword v2, v6, s[18:19]
	s_add_u32 s18, s18, 0x20000
	s_addc_u32 s19, s19, 0
	v_lshlrev_b32_e32 v40, 16, v35
	v_and_b32_e32 v41, 0xffff0000, v35
	v_fma_f32 v4, v4, s21, v40
	v_fma_f32 v5, v5, s21, v41
	v_cvt_pk_bf16_f32 v6, v4, v5
	global_store_dword v2, v6, s[18:19]
	s_add_u32 s18, s18, 0x20000
	s_addc_u32 s19, s19, 0
	v_lshlrev_b32_e32 v40, 16, v36
	v_and_b32_e32 v41, 0xffff0000, v36
	v_fma_f32 v4, v4, s21, v40
	v_fma_f32 v5, v5, s21, v41
	v_cvt_pk_bf16_f32 v6, v4, v5
	global_store_dword v2, v6, s[18:19]
	s_add_u32 s18, s18, 0x20000
	s_addc_u32 s19, s19, 0
	v_lshlrev_b32_e32 v40, 16, v37
	v_and_b32_e32 v41, 0xffff0000, v37
	v_fma_f32 v4, v4, s21, v40
	v_fma_f32 v5, v5, s21, v41
	v_cvt_pk_bf16_f32 v6, v4, v5
	global_store_dword v2, v6, s[18:19]
	s_add_u32 s18, s18, 0x20000
	s_addc_u32 s19, s19, 0
	v_lshlrev_b32_e32 v40, 16, v38
	v_and_b32_e32 v41, 0xffff0000, v38
	v_fma_f32 v4, v4, s21, v40
	v_fma_f32 v5, v5, s21, v41
	v_cvt_pk_bf16_f32 v6, v4, v5
	global_store_dword v2, v6, s[18:19]
	s_add_u32 s18, s18, 0x20000
	s_addc_u32 s19, s19, 0
	v_lshlrev_b32_e32 v40, 16, v39
	v_and_b32_e32 v41, 0xffff0000, v39
	v_fma_f32 v4, v4, s21, v40
	v_fma_f32 v5, v5, s21, v41
	global_load_dword v32, v2, s[16:17] nt
	s_add_u32 s16, s16, 0x20000
	s_addc_u32 s17, s17, 0
	global_load_dword v33, v2, s[16:17] nt
	s_add_u32 s16, s16, 0x20000
	s_addc_u32 s17, s17, 0
	global_load_dword v34, v2, s[16:17] nt
	s_add_u32 s16, s16, 0x20000
	s_addc_u32 s17, s17, 0
	global_load_dword v35, v2, s[16:17] nt
	s_add_u32 s16, s16, 0x20000
	s_addc_u32 s17, s17, 0
	global_load_dword v36, v2, s[16:17] nt
	s_add_u32 s16, s16, 0x20000
	s_addc_u32 s17, s17, 0
	global_load_dword v37, v2, s[16:17] nt
	s_add_u32 s16, s16, 0x20000
	s_addc_u32 s17, s17, 0
	global_load_dword v38, v2, s[16:17] nt
	s_add_u32 s16, s16, 0x20000
	s_addc_u32 s17, s17, 0
	global_load_dword v39, v2, s[16:17] nt
	s_add_u32 s16, s16, 0x20000
	s_addc_u32 s17, s17, 0
	s_mov_b32 s22, 6
.Lp3_ret_loop:
	s_waitcnt vmcnt(48)
	v_cvt_pk_bf16_f32 v6, v4, v5
	global_store_dword v2, v6, s[18:19]
	s_add_u32 s18, s18, 0x20000
	s_addc_u32 s19, s19, 0
	v_lshlrev_b32_e32 v40, 16, v8
	v_and_b32_e32 v41, 0xffff0000, v8
	v_fma_f32 v4, v4, s21, v40
	v_fma_f32 v5, v5, s21, v41
	v_cvt_pk_bf16_f32 v6, v4, v5
	global_store_dword v2, v6, s[18:19]
	s_add_u32 s18, s18, 0x20000
	s_addc_u32 s19, s19, 0
	v_lshlrev_b32_e32 v40, 16, v9
	v_and_b32_e32 v41, 0xffff0000, v9
	v_fma_f32 v4, v4, s21, v40
	v_fma_f32 v5, v5, s21, v41
	v_cvt_pk_bf16_f32 v6, v4, v5
	global_store_dword v2, v6, s[18:19]
	s_add_u32 s18, s18, 0x20000
	s_addc_u32 s19, s19, 0
	v_lshlrev_b32_e32 v40, 16, v10
	v_and_b32_e32 v41, 0xffff0000, v10
	v_fma_f32 v4, v4, s21, v40
	v_fma_f32 v5, v5, s21, v41
	v_cvt_pk_bf16_f32 v6, v4, v5
	global_store_dword v2, v6, s[18:19]
	s_add_u32 s18, s18, 0x20000
	s_addc_u32 s19, s19, 0
	v_lshlrev_b32_e32 v40, 16, v11
	v_and_b32_e32 v41, 0xffff0000, v11
	v_fma_f32 v4, v4, s21, v40
	v_fma_f32 v5, v5, s21, v41
	v_cvt_pk_bf16_f32 v6, v4, v5
	global_store_dword v2, v6, s[18:19]
	s_add_u32 s18, s18, 0x20000
	s_addc_u32 s19, s19, 0
	v_lshlrev_b32_e32 v40, 16, v12
	v_and_b32_e32 v41, 0xffff0000, v12
	v_fma_f32 v4, v4, s21, v40
	v_fma_f32 v5, v5, s21, v41
	v_cvt_pk_bf16_f32 v6, v4, v5
	global_store_dword v2, v6, s[18:19]
	s_add_u32 s18, s18, 0x20000
	s_addc_u32 s19, s19, 0
	v_lshlrev_b32_e32 v40, 16, v13
	v_and_b32_e32 v41, 0xffff0000, v13
	v_fma_f32 v4, v4, s21, v40
	v_fma_f32 v5, v5, s21, v41
	v_cvt_pk_bf16_f32 v6, v4, v5
	global_store_dword v2, v6, s[18:19]
	s_add_u32 s18, s18, 0x20000
	s_addc_u32 s19, s19, 0
	v_lshlrev_b32_e32 v40, 16, v14
	v_and_b32_e32 v41, 0xffff0000, v14
	v_fma_f32 v4, v4, s21, v40
	v_fma_f32 v5, v5, s21, v41
	v_cvt_pk_bf16_f32 v6, v4, v5
	global_store_dword v2, v6, s[18:19]
	s_add_u32 s18, s18, 0x20000
	s_addc_u32 s19, s19, 0
	v_lshlrev_b32_e32 v40, 16, v15
	v_and_b32_e32 v41, 0xffff0000, v15
	v_fma_f32 v4, v4, s21, v40
	v_fma_f32 v5, v5, s21, v41
	global_load_dword v8, v2, s[16:17] nt
	s_add_u32 s16, s16, 0x20000
	s_addc_u32 s17, s17, 0
	global_load_dword v9, v2, s[16:17] nt
	s_add_u32 s16, s16, 0x20000
	s_addc_u32 s17, s17, 0
	global_load_dword v10, v2, s[16:17] nt
	s_add_u32 s16, s16, 0x20000
	s_addc_u32 s17, s17, 0
	global_load_dword v11, v2, s[16:17] nt
	s_add_u32 s16, s16, 0x20000
	s_addc_u32 s17, s17, 0
	global_load_dword v12, v2, s[16:17] nt
	s_add_u32 s16, s16, 0x20000
	s_addc_u32 s17, s17, 0
	global_load_dword v13, v2, s[16:17] nt
	s_add_u32 s16, s16, 0x20000
	s_addc_u32 s17, s17, 0
	global_load_dword v14, v2, s[16:17] nt
	s_add_u32 s16, s16, 0x20000
	s_addc_u32 s17, s17, 0
	global_load_dword v15, v2, s[16:17] nt
	s_add_u32 s16, s16, 0x20000
	s_addc_u32 s17, s17, 0
	s_waitcnt vmcnt(48)
	v_cvt_pk_bf16_f32 v6, v4, v5
	global_store_dword v2, v6, s[18:19]
	s_add_u32 s18, s18, 0x20000
	s_addc_u32 s19, s19, 0
	v_lshlrev_b32_e32 v40, 16, v16
	v_and_b32_e32 v41, 0xffff0000, v16
	v_fma_f32 v4, v4, s21, v40
	v_fma_f32 v5, v5, s21, v41
	v_cvt_pk_bf16_f32 v6, v4, v5
	global_store_dword v2, v6, s[18:19]
	s_add_u32 s18, s18, 0x20000
	s_addc_u32 s19, s19, 0
	v_lshlrev_b32_e32 v40, 16, v17
	v_and_b32_e32 v41, 0xffff0000, v17
	v_fma_f32 v4, v4, s21, v40
	v_fma_f32 v5, v5, s21, v41
	v_cvt_pk_bf16_f32 v6, v4, v5
	global_store_dword v2, v6, s[18:19]
	s_add_u32 s18, s18, 0x20000
	s_addc_u32 s19, s19, 0
	v_lshlrev_b32_e32 v40, 16, v18
	v_and_b32_e32 v41, 0xffff0000, v18
	v_fma_f32 v4, v4, s21, v40
	v_fma_f32 v5, v5, s21, v41
	v_cvt_pk_bf16_f32 v6, v4, v5
	global_store_dword v2, v6, s[18:19]
	s_add_u32 s18, s18, 0x20000
	s_addc_u32 s19, s19, 0
	v_lshlrev_b32_e32 v40, 16, v19
	v_and_b32_e32 v41, 0xffff0000, v19
	v_fma_f32 v4, v4, s21, v40
	v_fma_f32 v5, v5, s21, v41
	v_cvt_pk_bf16_f32 v6, v4, v5
	global_store_dword v2, v6, s[18:19]
	s_add_u32 s18, s18, 0x20000
	s_addc_u32 s19, s19, 0
	v_lshlrev_b32_e32 v40, 16, v20
	v_and_b32_e32 v41, 0xffff0000, v20
	v_fma_f32 v4, v4, s21, v40
	v_fma_f32 v5, v5, s21, v41
	v_cvt_pk_bf16_f32 v6, v4, v5
	global_store_dword v2, v6, s[18:19]
	s_add_u32 s18, s18, 0x20000
	s_addc_u32 s19, s19, 0
	v_lshlrev_b32_e32 v40, 16, v21
	v_and_b32_e32 v41, 0xffff0000, v21
	v_fma_f32 v4, v4, s21, v40
	v_fma_f32 v5, v5, s21, v41
	v_cvt_pk_bf16_f32 v6, v4, v5
	global_store_dword v2, v6, s[18:19]
	s_add_u32 s18, s18, 0x20000
	s_addc_u32 s19, s19, 0
	v_lshlrev_b32_e32 v40, 16, v22
	v_and_b32_e32 v41, 0xffff0000, v22
	v_fma_f32 v4, v4, s21, v40
	v_fma_f32 v5, v5, s21, v41
	v_cvt_pk_bf16_f32 v6, v4, v5
	global_store_dword v2, v6, s[18:19]
	s_add_u32 s18, s18, 0x20000
	s_addc_u32 s19, s19, 0
	v_lshlrev_b32_e32 v40, 16, v23
	v_and_b32_e32 v41, 0xffff0000, v23
	v_fma_f32 v4, v4, s21, v40
	v_fma_f32 v5, v5, s21, v41
	global_load_dword v16, v2, s[16:17] nt
	s_add_u32 s16, s16, 0x20000
	s_addc_u32 s17, s17, 0
	global_load_dword v17, v2, s[16:17] nt
	s_add_u32 s16, s16, 0x20000
	s_addc_u32 s17, s17, 0
	global_load_dword v18, v2, s[16:17] nt
	s_add_u32 s16, s16, 0x20000
	s_addc_u32 s17, s17, 0
	global_load_dword v19, v2, s[16:17] nt
	s_add_u32 s16, s16, 0x20000
	s_addc_u32 s17, s17, 0
	global_load_dword v20, v2, s[16:17] nt
	s_add_u32 s16, s16, 0x20000
	s_addc_u32 s17, s17, 0
	global_load_dword v21, v2, s[16:17] nt
	s_add_u32 s16, s16, 0x20000
	s_addc_u32 s17, s17, 0
	global_load_dword v22, v2, s[16:17] nt
	s_add_u32 s16, s16, 0x20000
	s_addc_u32 s17, s17, 0
	global_load_dword v23, v2, s[16:17] nt
	s_add_u32 s16, s16, 0x20000
	s_addc_u32 s17, s17, 0
	s_waitcnt vmcnt(48)
	v_cvt_pk_bf16_f32 v6, v4, v5
	global_store_dword v2, v6, s[18:19]
	s_add_u32 s18, s18, 0x20000
	s_addc_u32 s19, s19, 0
	v_lshlrev_b32_e32 v40, 16, v24
	v_and_b32_e32 v41, 0xffff0000, v24
	v_fma_f32 v4, v4, s21, v40
	v_fma_f32 v5, v5, s21, v41
	v_cvt_pk_bf16_f32 v6, v4, v5
	global_store_dword v2, v6, s[18:19]
	s_add_u32 s18, s18, 0x20000
	s_addc_u32 s19, s19, 0
	v_lshlrev_b32_e32 v40, 16, v25
	v_and_b32_e32 v41, 0xffff0000, v25
	v_fma_f32 v4, v4, s21, v40
	v_fma_f32 v5, v5, s21, v41
	v_cvt_pk_bf16_f32 v6, v4, v5
	global_store_dword v2, v6, s[18:19]
	s_add_u32 s18, s18, 0x20000
	s_addc_u32 s19, s19, 0
	v_lshlrev_b32_e32 v40, 16, v26
	v_and_b32_e32 v41, 0xffff0000, v26
	v_fma_f32 v4, v4, s21, v40
	v_fma_f32 v5, v5, s21, v41
	v_cvt_pk_bf16_f32 v6, v4, v5
	global_store_dword v2, v6, s[18:19]
	s_add_u32 s18, s18, 0x20000
	s_addc_u32 s19, s19, 0
	v_lshlrev_b32_e32 v40, 16, v27
	v_and_b32_e32 v41, 0xffff0000, v27
	v_fma_f32 v4, v4, s21, v40
	v_fma_f32 v5, v5, s21, v41
	v_cvt_pk_bf16_f32 v6, v4, v5
	global_store_dword v2, v6, s[18:19]
	s_add_u32 s18, s18, 0x20000
	s_addc_u32 s19, s19, 0
	v_lshlrev_b32_e32 v40, 16, v28
	v_and_b32_e32 v41, 0xffff0000, v28
	v_fma_f32 v4, v4, s21, v40
	v_fma_f32 v5, v5, s21, v41
	v_cvt_pk_bf16_f32 v6, v4, v5
	global_store_dword v2, v6, s[18:19]
	s_add_u32 s18, s18, 0x20000
	s_addc_u32 s19, s19, 0
	v_lshlrev_b32_e32 v40, 16, v29
	v_and_b32_e32 v41, 0xffff0000, v29
	v_fma_f32 v4, v4, s21, v40
	v_fma_f32 v5, v5, s21, v41
	v_cvt_pk_bf16_f32 v6, v4, v5
	global_store_dword v2, v6, s[18:19]
	s_add_u32 s18, s18, 0x20000
	s_addc_u32 s19, s19, 0
	v_lshlrev_b32_e32 v40, 16, v30
	v_and_b32_e32 v41, 0xffff0000, v30
	v_fma_f32 v4, v4, s21, v40
	v_fma_f32 v5, v5, s21, v41
	v_cvt_pk_bf16_f32 v6, v4, v5
	global_store_dword v2, v6, s[18:19]
	s_add_u32 s18, s18, 0x20000
	s_addc_u32 s19, s19, 0
	v_lshlrev_b32_e32 v40, 16, v31
	v_and_b32_e32 v41, 0xffff0000, v31
	v_fma_f32 v4, v4, s21, v40
	v_fma_f32 v5, v5, s21, v41
	global_load_dword v24, v2, s[16:17] nt
	s_add_u32 s16, s16, 0x20000
	s_addc_u32 s17, s17, 0
	global_load_dword v25, v2, s[16:17] nt
	s_add_u32 s16, s16, 0x20000
	s_addc_u32 s17, s17, 0
	global_load_dword v26, v2, s[16:17] nt
	s_add_u32 s16, s16, 0x20000
	s_addc_u32 s17, s17, 0
	global_load_dword v27, v2, s[16:17] nt
	s_add_u32 s16, s16, 0x20000
	s_addc_u32 s17, s17, 0
	global_load_dword v28, v2, s[16:17] nt
	s_add_u32 s16, s16, 0x20000
	s_addc_u32 s17, s17, 0
	global_load_dword v29, v2, s[16:17] nt
	s_add_u32 s16, s16, 0x20000
	s_addc_u32 s17, s17, 0
	global_load_dword v30, v2, s[16:17] nt
	s_add_u32 s16, s16, 0x20000
	s_addc_u32 s17, s17, 0
	global_load_dword v31, v2, s[16:17] nt
	s_add_u32 s16, s16, 0x20000
	s_addc_u32 s17, s17, 0
	s_waitcnt vmcnt(48)
	v_cvt_pk_bf16_f32 v6, v4, v5
	global_store_dword v2, v6, s[18:19]
	s_add_u32 s18, s18, 0x20000
	s_addc_u32 s19, s19, 0
	v_lshlrev_b32_e32 v40, 16, v32
	v_and_b32_e32 v41, 0xffff0000, v32
	v_fma_f32 v4, v4, s21, v40
	v_fma_f32 v5, v5, s21, v41
	v_cvt_pk_bf16_f32 v6, v4, v5
	global_store_dword v2, v6, s[18:19]
	s_add_u32 s18, s18, 0x20000
	s_addc_u32 s19, s19, 0
	v_lshlrev_b32_e32 v40, 16, v33
	v_and_b32_e32 v41, 0xffff0000, v33
	v_fma_f32 v4, v4, s21, v40
	v_fma_f32 v5, v5, s21, v41
	v_cvt_pk_bf16_f32 v6, v4, v5
	global_store_dword v2, v6, s[18:19]
	s_add_u32 s18, s18, 0x20000
	s_addc_u32 s19, s19, 0
	v_lshlrev_b32_e32 v40, 16, v34
	v_and_b32_e32 v41, 0xffff0000, v34
	v_fma_f32 v4, v4, s21, v40
	v_fma_f32 v5, v5, s21, v41
	v_cvt_pk_bf16_f32 v6, v4, v5
	global_store_dword v2, v6, s[18:19]
	s_add_u32 s18, s18, 0x20000
	s_addc_u32 s19, s19, 0
	v_lshlrev_b32_e32 v40, 16, v35
	v_and_b32_e32 v41, 0xffff0000, v35
	v_fma_f32 v4, v4, s21, v40
	v_fma_f32 v5, v5, s21, v41
	v_cvt_pk_bf16_f32 v6, v4, v5
	global_store_dword v2, v6, s[18:19]
	s_add_u32 s18, s18, 0x20000
	s_addc_u32 s19, s19, 0
	v_lshlrev_b32_e32 v40, 16, v36
	v_and_b32_e32 v41, 0xffff0000, v36
	v_fma_f32 v4, v4, s21, v40
	v_fma_f32 v5, v5, s21, v41
	v_cvt_pk_bf16_f32 v6, v4, v5
	global_store_dword v2, v6, s[18:19]
	s_add_u32 s18, s18, 0x20000
	s_addc_u32 s19, s19, 0
	v_lshlrev_b32_e32 v40, 16, v37
	v_and_b32_e32 v41, 0xffff0000, v37
	v_fma_f32 v4, v4, s21, v40
	v_fma_f32 v5, v5, s21, v41
	v_cvt_pk_bf16_f32 v6, v4, v5
	global_store_dword v2, v6, s[18:19]
	s_add_u32 s18, s18, 0x20000
	s_addc_u32 s19, s19, 0
	v_lshlrev_b32_e32 v40, 16, v38
	v_and_b32_e32 v41, 0xffff0000, v38
	v_fma_f32 v4, v4, s21, v40
	v_fma_f32 v5, v5, s21, v41
	v_cvt_pk_bf16_f32 v6, v4, v5
	global_store_dword v2, v6, s[18:19]
	s_add_u32 s18, s18, 0x20000
	s_addc_u32 s19, s19, 0
	v_lshlrev_b32_e32 v40, 16, v39
	v_and_b32_e32 v41, 0xffff0000, v39
	v_fma_f32 v4, v4, s21, v40
	v_fma_f32 v5, v5, s21, v41
	global_load_dword v32, v2, s[16:17] nt
	s_add_u32 s16, s16, 0x20000
	s_addc_u32 s17, s17, 0
	global_load_dword v33, v2, s[16:17] nt
	s_add_u32 s16, s16, 0x20000
	s_addc_u32 s17, s17, 0
	global_load_dword v34, v2, s[16:17] nt
	s_add_u32 s16, s16, 0x20000
	s_addc_u32 s17, s17, 0
	global_load_dword v35, v2, s[16:17] nt
	s_add_u32 s16, s16, 0x20000
	s_addc_u32 s17, s17, 0
	global_load_dword v36, v2, s[16:17] nt
	s_add_u32 s16, s16, 0x20000
	s_addc_u32 s17, s17, 0
	global_load_dword v37, v2, s[16:17] nt
	s_add_u32 s16, s16, 0x20000
	s_addc_u32 s17, s17, 0
	global_load_dword v38, v2, s[16:17] nt
	s_add_u32 s16, s16, 0x20000
	s_addc_u32 s17, s17, 0
	global_load_dword v39, v2, s[16:17] nt
	s_add_u32 s16, s16, 0x20000
	s_addc_u32 s17, s17, 0
	s_sub_u32 s22, s22, 1
	s_cmp_lg_u32 s22, 0
	s_cbranch_scc1 .Lp3_ret_loop
	s_waitcnt vmcnt(48)
	v_cvt_pk_bf16_f32 v6, v4, v5
	global_store_dword v2, v6, s[18:19]
	s_add_u32 s18, s18, 0x20000
	s_addc_u32 s19, s19, 0
	v_lshlrev_b32_e32 v40, 16, v8
	v_and_b32_e32 v41, 0xffff0000, v8
	v_fma_f32 v4, v4, s21, v40
	v_fma_f32 v5, v5, s21, v41
	v_cvt_pk_bf16_f32 v6, v4, v5
	global_store_dword v2, v6, s[18:19]
	s_add_u32 s18, s18, 0x20000
	s_addc_u32 s19, s19, 0
	v_lshlrev_b32_e32 v40, 16, v9
	v_and_b32_e32 v41, 0xffff0000, v9
	v_fma_f32 v4, v4, s21, v40
	v_fma_f32 v5, v5, s21, v41
	v_cvt_pk_bf16_f32 v6, v4, v5
	global_store_dword v2, v6, s[18:19]
	s_add_u32 s18, s18, 0x20000
	s_addc_u32 s19, s19, 0
	v_lshlrev_b32_e32 v40, 16, v10
	v_and_b32_e32 v41, 0xffff0000, v10
	v_fma_f32 v4, v4, s21, v40
	v_fma_f32 v5, v5, s21, v41
	v_cvt_pk_bf16_f32 v6, v4, v5
	global_store_dword v2, v6, s[18:19]
	s_add_u32 s18, s18, 0x20000
	s_addc_u32 s19, s19, 0
	v_lshlrev_b32_e32 v40, 16, v11
	v_and_b32_e32 v41, 0xffff0000, v11
	v_fma_f32 v4, v4, s21, v40
	v_fma_f32 v5, v5, s21, v41
	v_cvt_pk_bf16_f32 v6, v4, v5
	global_store_dword v2, v6, s[18:19]
	s_add_u32 s18, s18, 0x20000
	s_addc_u32 s19, s19, 0
	v_lshlrev_b32_e32 v40, 16, v12
	v_and_b32_e32 v41, 0xffff0000, v12
	v_fma_f32 v4, v4, s21, v40
	v_fma_f32 v5, v5, s21, v41
	v_cvt_pk_bf16_f32 v6, v4, v5
	global_store_dword v2, v6, s[18:19]
	s_add_u32 s18, s18, 0x20000
	s_addc_u32 s19, s19, 0
	v_lshlrev_b32_e32 v40, 16, v13
	v_and_b32_e32 v41, 0xffff0000, v13
	v_fma_f32 v4, v4, s21, v40
	v_fma_f32 v5, v5, s21, v41
	v_cvt_pk_bf16_f32 v6, v4, v5
	global_store_dword v2, v6, s[18:19]
	s_add_u32 s18, s18, 0x20000
	s_addc_u32 s19, s19, 0
	v_lshlrev_b32_e32 v40, 16, v14
	v_and_b32_e32 v41, 0xffff0000, v14
	v_fma_f32 v4, v4, s21, v40
	v_fma_f32 v5, v5, s21, v41
	v_cvt_pk_bf16_f32 v6, v4, v5
	global_store_dword v2, v6, s[18:19]
	s_add_u32 s18, s18, 0x20000
	s_addc_u32 s19, s19, 0
	v_lshlrev_b32_e32 v40, 16, v15
	v_and_b32_e32 v41, 0xffff0000, v15
	v_fma_f32 v4, v4, s21, v40
	v_fma_f32 v5, v5, s21, v41
	s_waitcnt vmcnt(40)
	v_cvt_pk_bf16_f32 v6, v4, v5
	global_store_dword v2, v6, s[18:19]
	s_add_u32 s18, s18, 0x20000
	s_addc_u32 s19, s19, 0
	v_lshlrev_b32_e32 v40, 16, v16
	v_and_b32_e32 v41, 0xffff0000, v16
	v_fma_f32 v4, v4, s21, v40
	v_fma_f32 v5, v5, s21, v41
	v_cvt_pk_bf16_f32 v6, v4, v5
	global_store_dword v2, v6, s[18:19]
	s_add_u32 s18, s18, 0x20000
	s_addc_u32 s19, s19, 0
	v_lshlrev_b32_e32 v40, 16, v17
	v_and_b32_e32 v41, 0xffff0000, v17
	v_fma_f32 v4, v4, s21, v40
	v_fma_f32 v5, v5, s21, v41
	v_cvt_pk_bf16_f32 v6, v4, v5
	global_store_dword v2, v6, s[18:19]
	s_add_u32 s18, s18, 0x20000
	s_addc_u32 s19, s19, 0
	v_lshlrev_b32_e32 v40, 16, v18
	v_and_b32_e32 v41, 0xffff0000, v18
	v_fma_f32 v4, v4, s21, v40
	v_fma_f32 v5, v5, s21, v41
	v_cvt_pk_bf16_f32 v6, v4, v5
	global_store_dword v2, v6, s[18:19]
	s_add_u32 s18, s18, 0x20000
	s_addc_u32 s19, s19, 0
	v_lshlrev_b32_e32 v40, 16, v19
	v_and_b32_e32 v41, 0xffff0000, v19
	v_fma_f32 v4, v4, s21, v40
	v_fma_f32 v5, v5, s21, v41
	v_cvt_pk_bf16_f32 v6, v4, v5
	global_store_dword v2, v6, s[18:19]
	s_add_u32 s18, s18, 0x20000
	s_addc_u32 s19, s19, 0
	v_lshlrev_b32_e32 v40, 16, v20
	v_and_b32_e32 v41, 0xffff0000, v20
	v_fma_f32 v4, v4, s21, v40
	v_fma_f32 v5, v5, s21, v41
	v_cvt_pk_bf16_f32 v6, v4, v5
	global_store_dword v2, v6, s[18:19]
	s_add_u32 s18, s18, 0x20000
	s_addc_u32 s19, s19, 0
	v_lshlrev_b32_e32 v40, 16, v21
	v_and_b32_e32 v41, 0xffff0000, v21
	v_fma_f32 v4, v4, s21, v40
	v_fma_f32 v5, v5, s21, v41
	v_cvt_pk_bf16_f32 v6, v4, v5
	global_store_dword v2, v6, s[18:19]
	s_add_u32 s18, s18, 0x20000
	s_addc_u32 s19, s19, 0
	v_lshlrev_b32_e32 v40, 16, v22
	v_and_b32_e32 v41, 0xffff0000, v22
	v_fma_f32 v4, v4, s21, v40
	v_fma_f32 v5, v5, s21, v41
	v_cvt_pk_bf16_f32 v6, v4, v5
	global_store_dword v2, v6, s[18:19]
	s_add_u32 s18, s18, 0x20000
	s_addc_u32 s19, s19, 0
	v_lshlrev_b32_e32 v40, 16, v23
	v_and_b32_e32 v41, 0xffff0000, v23
	v_fma_f32 v4, v4, s21, v40
	v_fma_f32 v5, v5, s21, v41
	s_waitcnt vmcnt(32)
	v_cvt_pk_bf16_f32 v6, v4, v5
	global_store_dword v2, v6, s[18:19]
	s_add_u32 s18, s18, 0x20000
	s_addc_u32 s19, s19, 0
	v_lshlrev_b32_e32 v40, 16, v24
	v_and_b32_e32 v41, 0xffff0000, v24
	v_fma_f32 v4, v4, s21, v40
	v_fma_f32 v5, v5, s21, v41
	v_cvt_pk_bf16_f32 v6, v4, v5
	global_store_dword v2, v6, s[18:19]
	s_add_u32 s18, s18, 0x20000
	s_addc_u32 s19, s19, 0
	v_lshlrev_b32_e32 v40, 16, v25
	v_and_b32_e32 v41, 0xffff0000, v25
	v_fma_f32 v4, v4, s21, v40
	v_fma_f32 v5, v5, s21, v41
	v_cvt_pk_bf16_f32 v6, v4, v5
	global_store_dword v2, v6, s[18:19]
	s_add_u32 s18, s18, 0x20000
	s_addc_u32 s19, s19, 0
	v_lshlrev_b32_e32 v40, 16, v26
	v_and_b32_e32 v41, 0xffff0000, v26
	v_fma_f32 v4, v4, s21, v40
	v_fma_f32 v5, v5, s21, v41
	v_cvt_pk_bf16_f32 v6, v4, v5
	global_store_dword v2, v6, s[18:19]
	s_add_u32 s18, s18, 0x20000
	s_addc_u32 s19, s19, 0
	v_lshlrev_b32_e32 v40, 16, v27
	v_and_b32_e32 v41, 0xffff0000, v27
	v_fma_f32 v4, v4, s21, v40
	v_fma_f32 v5, v5, s21, v41
	v_cvt_pk_bf16_f32 v6, v4, v5
	global_store_dword v2, v6, s[18:19]
	s_add_u32 s18, s18, 0x20000
	s_addc_u32 s19, s19, 0
	v_lshlrev_b32_e32 v40, 16, v28
	v_and_b32_e32 v41, 0xffff0000, v28
	v_fma_f32 v4, v4, s21, v40
	v_fma_f32 v5, v5, s21, v41
	v_cvt_pk_bf16_f32 v6, v4, v5
	global_store_dword v2, v6, s[18:19]
	s_add_u32 s18, s18, 0x20000
	s_addc_u32 s19, s19, 0
	v_lshlrev_b32_e32 v40, 16, v29
	v_and_b32_e32 v41, 0xffff0000, v29
	v_fma_f32 v4, v4, s21, v40
	v_fma_f32 v5, v5, s21, v41
	v_cvt_pk_bf16_f32 v6, v4, v5
	global_store_dword v2, v6, s[18:19]
	s_add_u32 s18, s18, 0x20000
	s_addc_u32 s19, s19, 0
	v_lshlrev_b32_e32 v40, 16, v30
	v_and_b32_e32 v41, 0xffff0000, v30
	v_fma_f32 v4, v4, s21, v40
	v_fma_f32 v5, v5, s21, v41
	v_cvt_pk_bf16_f32 v6, v4, v5
	global_store_dword v2, v6, s[18:19]
	s_add_u32 s18, s18, 0x20000
	s_addc_u32 s19, s19, 0
	v_lshlrev_b32_e32 v40, 16, v31
	v_and_b32_e32 v41, 0xffff0000, v31
	v_fma_f32 v4, v4, s21, v40
	v_fma_f32 v5, v5, s21, v41
	s_waitcnt vmcnt(24)
	v_cvt_pk_bf16_f32 v6, v4, v5
	global_store_dword v2, v6, s[18:19]
	s_add_u32 s18, s18, 0x20000
	s_addc_u32 s19, s19, 0
	v_lshlrev_b32_e32 v40, 16, v32
	v_and_b32_e32 v41, 0xffff0000, v32
	v_fma_f32 v4, v4, s21, v40
	v_fma_f32 v5, v5, s21, v41
	v_cvt_pk_bf16_f32 v6, v4, v5
	global_store_dword v2, v6, s[18:19]
	s_add_u32 s18, s18, 0x20000
	s_addc_u32 s19, s19, 0
	v_lshlrev_b32_e32 v40, 16, v33
	v_and_b32_e32 v41, 0xffff0000, v33
	v_fma_f32 v4, v4, s21, v40
	v_fma_f32 v5, v5, s21, v41
	v_cvt_pk_bf16_f32 v6, v4, v5
	global_store_dword v2, v6, s[18:19]
	s_add_u32 s18, s18, 0x20000
	s_addc_u32 s19, s19, 0
	v_lshlrev_b32_e32 v40, 16, v34
	v_and_b32_e32 v41, 0xffff0000, v34
	v_fma_f32 v4, v4, s21, v40
	v_fma_f32 v5, v5, s21, v41
	v_cvt_pk_bf16_f32 v6, v4, v5
	global_store_dword v2, v6, s[18:19]
	s_add_u32 s18, s18, 0x20000
	s_addc_u32 s19, s19, 0
	v_lshlrev_b32_e32 v40, 16, v35
	v_and_b32_e32 v41, 0xffff0000, v35
	v_fma_f32 v4, v4, s21, v40
	v_fma_f32 v5, v5, s21, v41
	v_cvt_pk_bf16_f32 v6, v4, v5
	global_store_dword v2, v6, s[18:19]
	s_add_u32 s18, s18, 0x20000
	s_addc_u32 s19, s19, 0
	v_lshlrev_b32_e32 v40, 16, v36
	v_and_b32_e32 v41, 0xffff0000, v36
	v_fma_f32 v4, v4, s21, v40
	v_fma_f32 v5, v5, s21, v41
	v_cvt_pk_bf16_f32 v6, v4, v5
	global_store_dword v2, v6, s[18:19]
	s_add_u32 s18, s18, 0x20000
	s_addc_u32 s19, s19, 0
	v_lshlrev_b32_e32 v40, 16, v37
	v_and_b32_e32 v41, 0xffff0000, v37
	v_fma_f32 v4, v4, s21, v40
	v_fma_f32 v5, v5, s21, v41
	v_cvt_pk_bf16_f32 v6, v4, v5
	global_store_dword v2, v6, s[18:19]
	s_add_u32 s18, s18, 0x20000
	s_addc_u32 s19, s19, 0
	v_lshlrev_b32_e32 v40, 16, v38
	v_and_b32_e32 v41, 0xffff0000, v38
	v_fma_f32 v4, v4, s21, v40
	v_fma_f32 v5, v5, s21, v41
	v_cvt_pk_bf16_f32 v6, v4, v5
	global_store_dword v2, v6, s[18:19]
	s_add_u32 s18, s18, 0x20000
	s_addc_u32 s19, s19, 0
	v_lshlrev_b32_e32 v40, 16, v39
	v_and_b32_e32 v41, 0xffff0000, v39
	v_fma_f32 v4, v4, s21, v40
	v_fma_f32 v5, v5, s21, v41
	s_branch .Lp3_done
.Lp3_ssd:
	s_add_u32 s16, s8, s15
	s_addc_u32 s17, s9, 0
	s_add_u32 s16, s16, 0x4000000
	s_addc_u32 s17, s17, 0
	s_mov_b64 s[18:19], s[16:17]
	v_add_u32_e32 v1, 0xffff8000, v1
	v_lshlrev_b32_e32 v2, 2, v1
	s_sub_u32 s20, s14, 0x8000
	s_lshr_b32 s20, s20, 12
	s_lshl_b32 s23, s13, 11
	s_add_u32 s20, s20, s23
	s_lshl_b32 s20, s20, 2
	s_add_u32 s24, s10, 0x3f2a000
	s_addc_u32 s25, s11, 0
	s_add_u32 s24, s24, s20
	s_addc_u32 s25, s25, 0
	v_mov_b32_e32 v4, 0
	v_mov_b32_e32 v5, 0
	global_load_dword v8, v2, s[16:17] nt
	s_add_u32 s16, s16, 0x20000
	s_addc_u32 s17, s17, 0
	global_load_dword v9, v2, s[16:17] nt
	s_add_u32 s16, s16, 0x20000
	s_addc_u32 s17, s17, 0
	global_load_dword v10, v2, s[16:17] nt
	s_add_u32 s16, s16, 0x20000
	s_addc_u32 s17, s17, 0
	global_load_dword v11, v2, s[16:17] nt
	s_add_u32 s16, s16, 0x20000
	s_addc_u32 s17, s17, 0
	global_load_dword v12, v2, s[16:17] nt
	s_add_u32 s16, s16, 0x20000
	s_addc_u32 s17, s17, 0
	global_load_dword v13, v2, s[16:17] nt
	s_add_u32 s16, s16, 0x20000
	s_addc_u32 s17, s17, 0
	global_load_dword v14, v2, s[16:17] nt
	s_add_u32 s16, s16, 0x20000
	s_addc_u32 s17, s17, 0
	global_load_dword v15, v2, s[16:17] nt
	s_add_u32 s16, s16, 0x20000
	s_addc_u32 s17, s17, 0
	s_load_dword s32, s[24:25], 0x0
	s_load_dword s33, s[24:25], 0x20
	s_load_dword s34, s[24:25], 0x40
	s_load_dword s35, s[24:25], 0x60
	s_load_dword s36, s[24:25], 0x80
	s_load_dword s37, s[24:25], 0xa0
	s_load_dword s38, s[24:25], 0xc0
	s_load_dword s39, s[24:25], 0xe0
	s_add_u32 s24, s24, 0x100
	s_addc_u32 s25, s25, 0
	global_load_dword v16, v2, s[16:17] nt
	s_add_u32 s16, s16, 0x20000
	s_addc_u32 s17, s17, 0
	global_load_dword v17, v2, s[16:17] nt
	s_add_u32 s16, s16, 0x20000
	s_addc_u32 s17, s17, 0
	global_load_dword v18, v2, s[16:17] nt
	s_add_u32 s16, s16, 0x20000
	s_addc_u32 s17, s17, 0
	global_load_dword v19, v2, s[16:17] nt
	s_add_u32 s16, s16, 0x20000
	s_addc_u32 s17, s17, 0
	global_load_dword v20, v2, s[16:17] nt
	s_add_u32 s16, s16, 0x20000
	s_addc_u32 s17, s17, 0
	global_load_dword v21, v2, s[16:17] nt
	s_add_u32 s16, s16, 0x20000
	s_addc_u32 s17, s17, 0
	global_load_dword v22, v2, s[16:17] nt
	s_add_u32 s16, s16, 0x20000
	s_addc_u32 s17, s17, 0
	global_load_dword v23, v2, s[16:17] nt
	s_add_u32 s16, s16, 0x20000
	s_addc_u32 s17, s17, 0
	s_load_dword s40, s[24:25], 0x0
	s_load_dword s41, s[24:25], 0x20
	s_load_dword s42, s[24:25], 0x40
	s_load_dword s43, s[24:25], 0x60
	s_load_dword s44, s[24:25], 0x80
	s_load_dword s45, s[24:25], 0xa0
	s_load_dword s46, s[24:25], 0xc0
	s_load_dword s47, s[24:25], 0xe0
	s_add_u32 s24, s24, 0x100
	s_addc_u32 s25, s25, 0
	global_load_dword v24, v2, s[16:17] nt
	s_add_u32 s16, s16, 0x20000
	s_addc_u32 s17, s17, 0
	global_load_dword v25, v2, s[16:17] nt
	s_add_u32 s16, s16, 0x20000
	s_addc_u32 s17, s17, 0
	global_load_dword v26, v2, s[16:17] nt
	s_add_u32 s16, s16, 0x20000
	s_addc_u32 s17, s17, 0
	global_load_dword v27, v2, s[16:17] nt
	s_add_u32 s16, s16, 0x20000
	s_addc_u32 s17, s17, 0
	global_load_dword v28, v2, s[16:17] nt
	s_add_u32 s16, s16, 0x20000
	s_addc_u32 s17, s17, 0
	global_load_dword v29, v2, s[16:17] nt
	s_add_u32 s16, s16, 0x20000
	s_addc_u32 s17, s17, 0
	global_load_dword v30, v2, s[16:17] nt
	s_add_u32 s16, s16, 0x20000
	s_addc_u32 s17, s17, 0
	global_load_dword v31, v2, s[16:17] nt
	s_add_u32 s16, s16, 0x20000
	s_addc_u32 s17, s17, 0
	s_load_dword s48, s[24:25], 0x0
	s_load_dword s49, s[24:25], 0x20
	s_load_dword s50, s[24:25], 0x40
	s_load_dword s51, s[24:25], 0x60
	s_load_dword s52, s[24:25], 0x80
	s_load_dword s53, s[24:25], 0xa0
	s_load_dword s54, s[24:25], 0xc0
	s_load_dword s55, s[24:25], 0xe0
	s_add_u32 s24, s24, 0x100
	s_addc_u32 s25, s25, 0
	global_load_dword v32, v2, s[16:17] nt
	s_add_u32 s16, s16, 0x20000
	s_addc_u32 s17, s17, 0
	global_load_dword v33, v2, s[16:17] nt
	s_add_u32 s16, s16, 0x20000
	s_addc_u32 s17, s17, 0
	global_load_dword v34, v2, s[16:17] nt
	s_add_u32 s16, s16, 0x20000
	s_addc_u32 s17, s17, 0
	global_load_dword v35, v2, s[16:17] nt
	s_add_u32 s16, s16, 0x20000
	s_addc_u32 s17, s17, 0
	global_load_dword v36, v2, s[16:17] nt
	s_add_u32 s16, s16, 0x20000
	s_addc_u32 s17, s17, 0
	global_load_dword v37, v2, s[16:17] nt
	s_add_u32 s16, s16, 0x20000
	s_addc_u32 s17, s17, 0
	global_load_dword v38, v2, s[16:17] nt
	s_add_u32 s16, s16, 0x20000
	s_addc_u32 s17, s17, 0
	global_load_dword v39, v2, s[16:17] nt
	s_add_u32 s16, s16, 0x20000
	s_addc_u32 s17, s17, 0
	s_load_dword s56, s[24:25], 0x0
	s_load_dword s57, s[24:25], 0x20
	s_load_dword s58, s[24:25], 0x40
	s_load_dword s59, s[24:25], 0x60
	s_load_dword s60, s[24:25], 0x80
	s_load_dword s61, s[24:25], 0xa0
	s_load_dword s62, s[24:25], 0xc0
	s_load_dword s63, s[24:25], 0xe0
	s_add_u32 s24, s24, 0x100
	s_addc_u32 s25, s25, 0
	s_waitcnt vmcnt(24) lgkmcnt(0)
	v_cvt_pk_bf16_f32 v6, v4, v5
	global_store_dword v2, v6, s[18:19]
	s_add_u32 s18, s18, 0x20000
	s_addc_u32 s19, s19, 0
	v_lshlrev_b32_e32 v40, 16, v8
	v_and_b32_e32 v41, 0xffff0000, v8
	v_fma_f32 v4, v4, s32, v40
	v_fma_f32 v5, v5, s32, v41
	v_cvt_pk_bf16_f32 v6, v4, v5
	global_store_dword v2, v6, s[18:19]
	s_add_u32 s18, s18, 0x20000
	s_addc_u32 s19, s19, 0
	v_lshlrev_b32_e32 v40, 16, v9
	v_and_b32_e32 v41, 0xffff0000, v9
	v_fma_f32 v4, v4, s33, v40
	v_fma_f32 v5, v5, s33, v41
	v_cvt_pk_bf16_f32 v6, v4, v5
	global_store_dword v2, v6, s[18:19]
	s_add_u32 s18, s18, 0x20000
	s_addc_u32 s19, s19, 0
	v_lshlrev_b32_e32 v40, 16, v10
	v_and_b32_e32 v41, 0xffff0000, v10
	v_fma_f32 v4, v4, s34, v40
	v_fma_f32 v5, v5, s34, v41
	v_cvt_pk_bf16_f32 v6, v4, v5
	global_store_dword v2, v6, s[18:19]
	s_add_u32 s18, s18, 0x20000
	s_addc_u32 s19, s19, 0
	v_lshlrev_b32_e32 v40, 16, v11
	v_and_b32_e32 v41, 0xffff0000, v11
	v_fma_f32 v4, v4, s35, v40
	v_fma_f32 v5, v5, s35, v41
	v_cvt_pk_bf16_f32 v6, v4, v5
	global_store_dword v2, v6, s[18:19]
	s_add_u32 s18, s18, 0x20000
	s_addc_u32 s19, s19, 0
	v_lshlrev_b32_e32 v40, 16, v12
	v_and_b32_e32 v41, 0xffff0000, v12
	v_fma_f32 v4, v4, s36, v40
	v_fma_f32 v5, v5, s36, v41
	v_cvt_pk_bf16_f32 v6, v4, v5
	global_store_dword v2, v6, s[18:19]
	s_add_u32 s18, s18, 0x20000
	s_addc_u32 s19, s19, 0
	v_lshlrev_b32_e32 v40, 16, v13
	v_and_b32_e32 v41, 0xffff0000, v13
	v_fma_f32 v4, v4, s37, v40
	v_fma_f32 v5, v5, s37, v41
	v_cvt_pk_bf16_f32 v6, v4, v5
	global_store_dword v2, v6, s[18:19]
	s_add_u32 s18, s18, 0x20000
	s_addc_u32 s19, s19, 0
	v_lshlrev_b32_e32 v40, 16, v14
	v_and_b32_e32 v41, 0xffff0000, v14
	v_fma_f32 v4, v4, s38, v40
	v_fma_f32 v5, v5, s38, v41
	v_cvt_pk_bf16_f32 v6, v4, v5
	global_store_dword v2, v6, s[18:19]
	s_add_u32 s18, s18, 0x20000
	s_addc_u32 s19, s19, 0
	v_lshlrev_b32_e32 v40, 16, v15
	v_and_b32_e32 v41, 0xffff0000, v15
	v_fma_f32 v4, v4, s39, v40
	v_fma_f32 v5, v5, s39, v41
	global_load_dword v8, v2, s[16:17] nt
	s_add_u32 s16, s16, 0x20000
	s_addc_u32 s17, s17, 0
	global_load_dword v9, v2, s[16:17] nt
	s_add_u32 s16, s16, 0x20000
	s_addc_u32 s17, s17, 0
	global_load_dword v10, v2, s[16:17] nt
	s_add_u32 s16, s16, 0x20000
	s_addc_u32 s17, s17, 0
	global_load_dword v11, v2, s[16:17] nt
	s_add_u32 s16, s16, 0x20000
	s_addc_u32 s17, s17, 0
	global_load_dword v12, v2, s[16:17] nt
	s_add_u32 s16, s16, 0x20000
	s_addc_u32 s17, s17, 0
	global_load_dword v13, v2, s[16:17] nt
	s_add_u32 s16, s16, 0x20000
	s_addc_u32 s17, s17, 0
	global_load_dword v14, v2, s[16:17] nt
	s_add_u32 s16, s16, 0x20000
	s_addc_u32 s17, s17, 0
	global_load_dword v15, v2, s[16:17] nt
	s_add_u32 s16, s16, 0x20000
	s_addc_u32 s17, s17, 0
	s_load_dword s32, s[24:25], 0x0
	s_load_dword s33, s[24:25], 0x20
	s_load_dword s34, s[24:25], 0x40
	s_load_dword s35, s[24:25], 0x60
	s_load_dword s36, s[24:25], 0x80
	s_load_dword s37, s[24:25], 0xa0
	s_load_dword s38, s[24:25], 0xc0
	s_load_dword s39, s[24:25], 0xe0
	s_add_u32 s24, s24, 0x100
	s_addc_u32 s25, s25, 0
	s_waitcnt vmcnt(32) lgkmcnt(0)
	v_cvt_pk_bf16_f32 v6, v4, v5
	global_store_dword v2, v6, s[18:19]
	s_add_u32 s18, s18, 0x20000
	s_addc_u32 s19, s19, 0
	v_lshlrev_b32_e32 v40, 16, v16
	v_and_b32_e32 v41, 0xffff0000, v16
	v_fma_f32 v4, v4, s40, v40
	v_fma_f32 v5, v5, s40, v41
	v_cvt_pk_bf16_f32 v6, v4, v5
	global_store_dword v2, v6, s[18:19]
	s_add_u32 s18, s18, 0x20000
	s_addc_u32 s19, s19, 0
	v_lshlrev_b32_e32 v40, 16, v17
	v_and_b32_e32 v41, 0xffff0000, v17
	v_fma_f32 v4, v4, s41, v40
	v_fma_f32 v5, v5, s41, v41
	v_cvt_pk_bf16_f32 v6, v4, v5
	global_store_dword v2, v6, s[18:19]
	s_add_u32 s18, s18, 0x20000
	s_addc_u32 s19, s19, 0
	v_lshlrev_b32_e32 v40, 16, v18
	v_and_b32_e32 v41, 0xffff0000, v18
	v_fma_f32 v4, v4, s42, v40
	v_fma_f32 v5, v5, s42, v41
	v_cvt_pk_bf16_f32 v6, v4, v5
	global_store_dword v2, v6, s[18:19]
	s_add_u32 s18, s18, 0x20000
	s_addc_u32 s19, s19, 0
	v_lshlrev_b32_e32 v40, 16, v19
	v_and_b32_e32 v41, 0xffff0000, v19
	v_fma_f32 v4, v4, s43, v40
	v_fma_f32 v5, v5, s43, v41
	v_cvt_pk_bf16_f32 v6, v4, v5
	global_store_dword v2, v6, s[18:19]
	s_add_u32 s18, s18, 0x20000
	s_addc_u32 s19, s19, 0
	v_lshlrev_b32_e32 v40, 16, v20
	v_and_b32_e32 v41, 0xffff0000, v20
	v_fma_f32 v4, v4, s44, v40
	v_fma_f32 v5, v5, s44, v41
	v_cvt_pk_bf16_f32 v6, v4, v5
	global_store_dword v2, v6, s[18:19]
	s_add_u32 s18, s18, 0x20000
	s_addc_u32 s19, s19, 0
	v_lshlrev_b32_e32 v40, 16, v21
	v_and_b32_e32 v41, 0xffff0000, v21
	v_fma_f32 v4, v4, s45, v40
	v_fma_f32 v5, v5, s45, v41
	v_cvt_pk_bf16_f32 v6, v4, v5
	global_store_dword v2, v6, s[18:19]
	s_add_u32 s18, s18, 0x20000
	s_addc_u32 s19, s19, 0
	v_lshlrev_b32_e32 v40, 16, v22
	v_and_b32_e32 v41, 0xffff0000, v22
	v_fma_f32 v4, v4, s46, v40
	v_fma_f32 v5, v5, s46, v41
	v_cvt_pk_bf16_f32 v6, v4, v5
	global_store_dword v2, v6, s[18:19]
	s_add_u32 s18, s18, 0x20000
	s_addc_u32 s19, s19, 0
	v_lshlrev_b32_e32 v40, 16, v23
	v_and_b32_e32 v41, 0xffff0000, v23
	v_fma_f32 v4, v4, s47, v40
	v_fma_f32 v5, v5, s47, v41
	global_load_dword v16, v2, s[16:17] nt
	s_add_u32 s16, s16, 0x20000
	s_addc_u32 s17, s17, 0
	global_load_dword v17, v2, s[16:17] nt
	s_add_u32 s16, s16, 0x20000
	s_addc_u32 s17, s17, 0
	global_load_dword v18, v2, s[16:17] nt
	s_add_u32 s16, s16, 0x20000
	s_addc_u32 s17, s17, 0
	global_load_dword v19, v2, s[16:17] nt
	s_add_u32 s16, s16, 0x20000
	s_addc_u32 s17, s17, 0
	global_load_dword v20, v2, s[16:17] nt
	s_add_u32 s16, s16, 0x20000
	s_addc_u32 s17, s17, 0
	global_load_dword v21, v2, s[16:17] nt
	s_add_u32 s16, s16, 0x20000
	s_addc_u32 s17, s17, 0
	global_load_dword v22, v2, s[16:17] nt
	s_add_u32 s16, s16, 0x20000
	s_addc_u32 s17, s17, 0
	global_load_dword v23, v2, s[16:17] nt
	s_add_u32 s16, s16, 0x20000
	s_addc_u32 s17, s17, 0
	s_load_dword s40, s[24:25], 0x0
	s_load_dword s41, s[24:25], 0x20
	s_load_dword s42, s[24:25], 0x40
	s_load_dword s43, s[24:25], 0x60
	s_load_dword s44, s[24:25], 0x80
	s_load_dword s45, s[24:25], 0xa0
	s_load_dword s46, s[24:25], 0xc0
	s_load_dword s47, s[24:25], 0xe0
	s_add_u32 s24, s24, 0x100
	s_addc_u32 s25, s25, 0
	s_waitcnt vmcnt(40) lgkmcnt(0)
	v_cvt_pk_bf16_f32 v6, v4, v5
	global_store_dword v2, v6, s[18:19]
	s_add_u32 s18, s18, 0x20000
	s_addc_u32 s19, s19, 0
	v_lshlrev_b32_e32 v40, 16, v24
	v_and_b32_e32 v41, 0xffff0000, v24
	v_fma_f32 v4, v4, s48, v40
	v_fma_f32 v5, v5, s48, v41
	v_cvt_pk_bf16_f32 v6, v4, v5
	global_store_dword v2, v6, s[18:19]
	s_add_u32 s18, s18, 0x20000
	s_addc_u32 s19, s19, 0
	v_lshlrev_b32_e32 v40, 16, v25
	v_and_b32_e32 v41, 0xffff0000, v25
	v_fma_f32 v4, v4, s49, v40
	v_fma_f32 v5, v5, s49, v41
	v_cvt_pk_bf16_f32 v6, v4, v5
	global_store_dword v2, v6, s[18:19]
	s_add_u32 s18, s18, 0x20000
	s_addc_u32 s19, s19, 0
	v_lshlrev_b32_e32 v40, 16, v26
	v_and_b32_e32 v41, 0xffff0000, v26
	v_fma_f32 v4, v4, s50, v40
	v_fma_f32 v5, v5, s50, v41
	v_cvt_pk_bf16_f32 v6, v4, v5
	global_store_dword v2, v6, s[18:19]
	s_add_u32 s18, s18, 0x20000
	s_addc_u32 s19, s19, 0
	v_lshlrev_b32_e32 v40, 16, v27
	v_and_b32_e32 v41, 0xffff0000, v27
	v_fma_f32 v4, v4, s51, v40
	v_fma_f32 v5, v5, s51, v41
	v_cvt_pk_bf16_f32 v6, v4, v5
	global_store_dword v2, v6, s[18:19]
	s_add_u32 s18, s18, 0x20000
	s_addc_u32 s19, s19, 0
	v_lshlrev_b32_e32 v40, 16, v28
	v_and_b32_e32 v41, 0xffff0000, v28
	v_fma_f32 v4, v4, s52, v40
	v_fma_f32 v5, v5, s52, v41
	v_cvt_pk_bf16_f32 v6, v4, v5
	global_store_dword v2, v6, s[18:19]
	s_add_u32 s18, s18, 0x20000
	s_addc_u32 s19, s19, 0
	v_lshlrev_b32_e32 v40, 16, v29
	v_and_b32_e32 v41, 0xffff0000, v29
	v_fma_f32 v4, v4, s53, v40
	v_fma_f32 v5, v5, s53, v41
	v_cvt_pk_bf16_f32 v6, v4, v5
	global_store_dword v2, v6, s[18:19]
	s_add_u32 s18, s18, 0x20000
	s_addc_u32 s19, s19, 0
	v_lshlrev_b32_e32 v40, 16, v30
	v_and_b32_e32 v41, 0xffff0000, v30
	v_fma_f32 v4, v4, s54, v40
	v_fma_f32 v5, v5, s54, v41
	v_cvt_pk_bf16_f32 v6, v4, v5
	global_store_dword v2, v6, s[18:19]
	s_add_u32 s18, s18, 0x20000
	s_addc_u32 s19, s19, 0
	v_lshlrev_b32_e32 v40, 16, v31
	v_and_b32_e32 v41, 0xffff0000, v31
	v_fma_f32 v4, v4, s55, v40
	v_fma_f32 v5, v5, s55, v41
	global_load_dword v24, v2, s[16:17] nt
	s_add_u32 s16, s16, 0x20000
	s_addc_u32 s17, s17, 0
	global_load_dword v25, v2, s[16:17] nt
	s_add_u32 s16, s16, 0x20000
	s_addc_u32 s17, s17, 0
	global_load_dword v26, v2, s[16:17] nt
	s_add_u32 s16, s16, 0x20000
	s_addc_u32 s17, s17, 0
	global_load_dword v27, v2, s[16:17] nt
	s_add_u32 s16, s16, 0x20000
	s_addc_u32 s17, s17, 0
	global_load_dword v28, v2, s[16:17] nt
	s_add_u32 s16, s16, 0x20000
	s_addc_u32 s17, s17, 0
	global_load_dword v29, v2, s[16:17] nt
	s_add_u32 s16, s16, 0x20000
	s_addc_u32 s17, s17, 0
	global_load_dword v30, v2, s[16:17] nt
	s_add_u32 s16, s16, 0x20000
	s_addc_u32 s17, s17, 0
	global_load_dword v31, v2, s[16:17] nt
	s_add_u32 s16, s16, 0x20000
	s_addc_u32 s17, s17, 0
	s_load_dword s48, s[24:25], 0x0
	s_load_dword s49, s[24:25], 0x20
	s_load_dword s50, s[24:25], 0x40
	s_load_dword s51, s[24:25], 0x60
	s_load_dword s52, s[24:25], 0x80
	s_load_dword s53, s[24:25], 0xa0
	s_load_dword s54, s[24:25], 0xc0
	s_load_dword s55, s[24:25], 0xe0
	s_add_u32 s24, s24, 0x100
	s_addc_u32 s25, s25, 0
	s_waitcnt vmcnt(48) lgkmcnt(0)
	v_cvt_pk_bf16_f32 v6, v4, v5
	global_store_dword v2, v6, s[18:19]
	s_add_u32 s18, s18, 0x20000
	s_addc_u32 s19, s19, 0
	v_lshlrev_b32_e32 v40, 16, v32
	v_and_b32_e32 v41, 0xffff0000, v32
	v_fma_f32 v4, v4, s56, v40
	v_fma_f32 v5, v5, s56, v41
	v_cvt_pk_bf16_f32 v6, v4, v5
	global_store_dword v2, v6, s[18:19]
	s_add_u32 s18, s18, 0x20000
	s_addc_u32 s19, s19, 0
	v_lshlrev_b32_e32 v40, 16, v33
	v_and_b32_e32 v41, 0xffff0000, v33
	v_fma_f32 v4, v4, s57, v40
	v_fma_f32 v5, v5, s57, v41
	v_cvt_pk_bf16_f32 v6, v4, v5
	global_store_dword v2, v6, s[18:19]
	s_add_u32 s18, s18, 0x20000
	s_addc_u32 s19, s19, 0
	v_lshlrev_b32_e32 v40, 16, v34
	v_and_b32_e32 v41, 0xffff0000, v34
	v_fma_f32 v4, v4, s58, v40
	v_fma_f32 v5, v5, s58, v41
	v_cvt_pk_bf16_f32 v6, v4, v5
	global_store_dword v2, v6, s[18:19]
	s_add_u32 s18, s18, 0x20000
	s_addc_u32 s19, s19, 0
	v_lshlrev_b32_e32 v40, 16, v35
	v_and_b32_e32 v41, 0xffff0000, v35
	v_fma_f32 v4, v4, s59, v40
	v_fma_f32 v5, v5, s59, v41
	v_cvt_pk_bf16_f32 v6, v4, v5
	global_store_dword v2, v6, s[18:19]
	s_add_u32 s18, s18, 0x20000
	s_addc_u32 s19, s19, 0
	v_lshlrev_b32_e32 v40, 16, v36
	v_and_b32_e32 v41, 0xffff0000, v36
	v_fma_f32 v4, v4, s60, v40
	v_fma_f32 v5, v5, s60, v41
	v_cvt_pk_bf16_f32 v6, v4, v5
	global_store_dword v2, v6, s[18:19]
	s_add_u32 s18, s18, 0x20000
	s_addc_u32 s19, s19, 0
	v_lshlrev_b32_e32 v40, 16, v37
	v_and_b32_e32 v41, 0xffff0000, v37
	v_fma_f32 v4, v4, s61, v40
	v_fma_f32 v5, v5, s61, v41
	v_cvt_pk_bf16_f32 v6, v4, v5
	global_store_dword v2, v6, s[18:19]
	s_add_u32 s18, s18, 0x20000
	s_addc_u32 s19, s19, 0
	v_lshlrev_b32_e32 v40, 16, v38
	v_and_b32_e32 v41, 0xffff0000, v38
	v_fma_f32 v4, v4, s62, v40
	v_fma_f32 v5, v5, s62, v41
	v_cvt_pk_bf16_f32 v6, v4, v5
	global_store_dword v2, v6, s[18:19]
	s_add_u32 s18, s18, 0x20000
	s_addc_u32 s19, s19, 0
	v_lshlrev_b32_e32 v40, 16, v39
	v_and_b32_e32 v41, 0xffff0000, v39
	v_fma_f32 v4, v4, s63, v40
	v_fma_f32 v5, v5, s63, v41
	global_load_dword v32, v2, s[16:17] nt
	s_add_u32 s16, s16, 0x20000
	s_addc_u32 s17, s17, 0
	global_load_dword v33, v2, s[16:17] nt
	s_add_u32 s16, s16, 0x20000
	s_addc_u32 s17, s17, 0
	global_load_dword v34, v2, s[16:17] nt
	s_add_u32 s16, s16, 0x20000
	s_addc_u32 s17, s17, 0
	global_load_dword v35, v2, s[16:17] nt
	s_add_u32 s16, s16, 0x20000
	s_addc_u32 s17, s17, 0
	global_load_dword v36, v2, s[16:17] nt
	s_add_u32 s16, s16, 0x20000
	s_addc_u32 s17, s17, 0
	global_load_dword v37, v2, s[16:17] nt
	s_add_u32 s16, s16, 0x20000
	s_addc_u32 s17, s17, 0
	global_load_dword v38, v2, s[16:17] nt
	s_add_u32 s16, s16, 0x20000
	s_addc_u32 s17, s17, 0
	global_load_dword v39, v2, s[16:17] nt
	s_add_u32 s16, s16, 0x20000
	s_addc_u32 s17, s17, 0
	s_load_dword s56, s[24:25], 0x0
	s_load_dword s57, s[24:25], 0x20
	s_load_dword s58, s[24:25], 0x40
	s_load_dword s59, s[24:25], 0x60
	s_load_dword s60, s[24:25], 0x80
	s_load_dword s61, s[24:25], 0xa0
	s_load_dword s62, s[24:25], 0xc0
	s_load_dword s63, s[24:25], 0xe0
	s_add_u32 s24, s24, 0x100
	s_addc_u32 s25, s25, 0
	s_mov_b32 s22, 6
.Lp3_ssd_loop:
	s_waitcnt vmcnt(48) lgkmcnt(0)
	v_cvt_pk_bf16_f32 v6, v4, v5
	global_store_dword v2, v6, s[18:19]
	s_add_u32 s18, s18, 0x20000
	s_addc_u32 s19, s19, 0
	v_lshlrev_b32_e32 v40, 16, v8
	v_and_b32_e32 v41, 0xffff0000, v8
	v_fma_f32 v4, v4, s32, v40
	v_fma_f32 v5, v5, s32, v41
	v_cvt_pk_bf16_f32 v6, v4, v5
	global_store_dword v2, v6, s[18:19]
	s_add_u32 s18, s18, 0x20000
	s_addc_u32 s19, s19, 0
	v_lshlrev_b32_e32 v40, 16, v9
	v_and_b32_e32 v41, 0xffff0000, v9
	v_fma_f32 v4, v4, s33, v40
	v_fma_f32 v5, v5, s33, v41
	v_cvt_pk_bf16_f32 v6, v4, v5
	global_store_dword v2, v6, s[18:19]
	s_add_u32 s18, s18, 0x20000
	s_addc_u32 s19, s19, 0
	v_lshlrev_b32_e32 v40, 16, v10
	v_and_b32_e32 v41, 0xffff0000, v10
	v_fma_f32 v4, v4, s34, v40
	v_fma_f32 v5, v5, s34, v41
	v_cvt_pk_bf16_f32 v6, v4, v5
	global_store_dword v2, v6, s[18:19]
	s_add_u32 s18, s18, 0x20000
	s_addc_u32 s19, s19, 0
	v_lshlrev_b32_e32 v40, 16, v11
	v_and_b32_e32 v41, 0xffff0000, v11
	v_fma_f32 v4, v4, s35, v40
	v_fma_f32 v5, v5, s35, v41
	v_cvt_pk_bf16_f32 v6, v4, v5
	global_store_dword v2, v6, s[18:19]
	s_add_u32 s18, s18, 0x20000
	s_addc_u32 s19, s19, 0
	v_lshlrev_b32_e32 v40, 16, v12
	v_and_b32_e32 v41, 0xffff0000, v12
	v_fma_f32 v4, v4, s36, v40
	v_fma_f32 v5, v5, s36, v41
	v_cvt_pk_bf16_f32 v6, v4, v5
	global_store_dword v2, v6, s[18:19]
	s_add_u32 s18, s18, 0x20000
	s_addc_u32 s19, s19, 0
	v_lshlrev_b32_e32 v40, 16, v13
	v_and_b32_e32 v41, 0xffff0000, v13
	v_fma_f32 v4, v4, s37, v40
	v_fma_f32 v5, v5, s37, v41
	v_cvt_pk_bf16_f32 v6, v4, v5
	global_store_dword v2, v6, s[18:19]
	s_add_u32 s18, s18, 0x20000
	s_addc_u32 s19, s19, 0
	v_lshlrev_b32_e32 v40, 16, v14
	v_and_b32_e32 v41, 0xffff0000, v14
	v_fma_f32 v4, v4, s38, v40
	v_fma_f32 v5, v5, s38, v41
	v_cvt_pk_bf16_f32 v6, v4, v5
	global_store_dword v2, v6, s[18:19]
	s_add_u32 s18, s18, 0x20000
	s_addc_u32 s19, s19, 0
	v_lshlrev_b32_e32 v40, 16, v15
	v_and_b32_e32 v41, 0xffff0000, v15
	v_fma_f32 v4, v4, s39, v40
	v_fma_f32 v5, v5, s39, v41
	global_load_dword v8, v2, s[16:17] nt
	s_add_u32 s16, s16, 0x20000
	s_addc_u32 s17, s17, 0
	global_load_dword v9, v2, s[16:17] nt
	s_add_u32 s16, s16, 0x20000
	s_addc_u32 s17, s17, 0
	global_load_dword v10, v2, s[16:17] nt
	s_add_u32 s16, s16, 0x20000
	s_addc_u32 s17, s17, 0
	global_load_dword v11, v2, s[16:17] nt
	s_add_u32 s16, s16, 0x20000
	s_addc_u32 s17, s17, 0
	global_load_dword v12, v2, s[16:17] nt
	s_add_u32 s16, s16, 0x20000
	s_addc_u32 s17, s17, 0
	global_load_dword v13, v2, s[16:17] nt
	s_add_u32 s16, s16, 0x20000
	s_addc_u32 s17, s17, 0
	global_load_dword v14, v2, s[16:17] nt
	s_add_u32 s16, s16, 0x20000
	s_addc_u32 s17, s17, 0
	global_load_dword v15, v2, s[16:17] nt
	s_add_u32 s16, s16, 0x20000
	s_addc_u32 s17, s17, 0
	s_load_dword s32, s[24:25], 0x0
	s_load_dword s33, s[24:25], 0x20
	s_load_dword s34, s[24:25], 0x40
	s_load_dword s35, s[24:25], 0x60
	s_load_dword s36, s[24:25], 0x80
	s_load_dword s37, s[24:25], 0xa0
	s_load_dword s38, s[24:25], 0xc0
	s_load_dword s39, s[24:25], 0xe0
	s_add_u32 s24, s24, 0x100
	s_addc_u32 s25, s25, 0
	s_waitcnt vmcnt(48) lgkmcnt(0)
	v_cvt_pk_bf16_f32 v6, v4, v5
	global_store_dword v2, v6, s[18:19]
	s_add_u32 s18, s18, 0x20000
	s_addc_u32 s19, s19, 0
	v_lshlrev_b32_e32 v40, 16, v16
	v_and_b32_e32 v41, 0xffff0000, v16
	v_fma_f32 v4, v4, s40, v40
	v_fma_f32 v5, v5, s40, v41
	v_cvt_pk_bf16_f32 v6, v4, v5
	global_store_dword v2, v6, s[18:19]
	s_add_u32 s18, s18, 0x20000
	s_addc_u32 s19, s19, 0
	v_lshlrev_b32_e32 v40, 16, v17
	v_and_b32_e32 v41, 0xffff0000, v17
	v_fma_f32 v4, v4, s41, v40
	v_fma_f32 v5, v5, s41, v41
	v_cvt_pk_bf16_f32 v6, v4, v5
	global_store_dword v2, v6, s[18:19]
	s_add_u32 s18, s18, 0x20000
	s_addc_u32 s19, s19, 0
	v_lshlrev_b32_e32 v40, 16, v18
	v_and_b32_e32 v41, 0xffff0000, v18
	v_fma_f32 v4, v4, s42, v40
	v_fma_f32 v5, v5, s42, v41
	v_cvt_pk_bf16_f32 v6, v4, v5
	global_store_dword v2, v6, s[18:19]
	s_add_u32 s18, s18, 0x20000
	s_addc_u32 s19, s19, 0
	v_lshlrev_b32_e32 v40, 16, v19
	v_and_b32_e32 v41, 0xffff0000, v19
	v_fma_f32 v4, v4, s43, v40
	v_fma_f32 v5, v5, s43, v41
	v_cvt_pk_bf16_f32 v6, v4, v5
	global_store_dword v2, v6, s[18:19]
	s_add_u32 s18, s18, 0x20000
	s_addc_u32 s19, s19, 0
	v_lshlrev_b32_e32 v40, 16, v20
	v_and_b32_e32 v41, 0xffff0000, v20
	v_fma_f32 v4, v4, s44, v40
	v_fma_f32 v5, v5, s44, v41
	v_cvt_pk_bf16_f32 v6, v4, v5
	global_store_dword v2, v6, s[18:19]
	s_add_u32 s18, s18, 0x20000
	s_addc_u32 s19, s19, 0
	v_lshlrev_b32_e32 v40, 16, v21
	v_and_b32_e32 v41, 0xffff0000, v21
	v_fma_f32 v4, v4, s45, v40
	v_fma_f32 v5, v5, s45, v41
	v_cvt_pk_bf16_f32 v6, v4, v5
	global_store_dword v2, v6, s[18:19]
	s_add_u32 s18, s18, 0x20000
	s_addc_u32 s19, s19, 0
	v_lshlrev_b32_e32 v40, 16, v22
	v_and_b32_e32 v41, 0xffff0000, v22
	v_fma_f32 v4, v4, s46, v40
	v_fma_f32 v5, v5, s46, v41
	v_cvt_pk_bf16_f32 v6, v4, v5
	global_store_dword v2, v6, s[18:19]
	s_add_u32 s18, s18, 0x20000
	s_addc_u32 s19, s19, 0
	v_lshlrev_b32_e32 v40, 16, v23
	v_and_b32_e32 v41, 0xffff0000, v23
	v_fma_f32 v4, v4, s47, v40
	v_fma_f32 v5, v5, s47, v41
	global_load_dword v16, v2, s[16:17] nt
	s_add_u32 s16, s16, 0x20000
	s_addc_u32 s17, s17, 0
	global_load_dword v17, v2, s[16:17] nt
	s_add_u32 s16, s16, 0x20000
	s_addc_u32 s17, s17, 0
	global_load_dword v18, v2, s[16:17] nt
	s_add_u32 s16, s16, 0x20000
	s_addc_u32 s17, s17, 0
	global_load_dword v19, v2, s[16:17] nt
	s_add_u32 s16, s16, 0x20000
	s_addc_u32 s17, s17, 0
	global_load_dword v20, v2, s[16:17] nt
	s_add_u32 s16, s16, 0x20000
	s_addc_u32 s17, s17, 0
	global_load_dword v21, v2, s[16:17] nt
	s_add_u32 s16, s16, 0x20000
	s_addc_u32 s17, s17, 0
	global_load_dword v22, v2, s[16:17] nt
	s_add_u32 s16, s16, 0x20000
	s_addc_u32 s17, s17, 0
	global_load_dword v23, v2, s[16:17] nt
	s_add_u32 s16, s16, 0x20000
	s_addc_u32 s17, s17, 0
	s_load_dword s40, s[24:25], 0x0
	s_load_dword s41, s[24:25], 0x20
	s_load_dword s42, s[24:25], 0x40
	s_load_dword s43, s[24:25], 0x60
	s_load_dword s44, s[24:25], 0x80
	s_load_dword s45, s[24:25], 0xa0
	s_load_dword s46, s[24:25], 0xc0
	s_load_dword s47, s[24:25], 0xe0
	s_add_u32 s24, s24, 0x100
	s_addc_u32 s25, s25, 0
	s_waitcnt vmcnt(48) lgkmcnt(0)
	v_cvt_pk_bf16_f32 v6, v4, v5
	global_store_dword v2, v6, s[18:19]
	s_add_u32 s18, s18, 0x20000
	s_addc_u32 s19, s19, 0
	v_lshlrev_b32_e32 v40, 16, v24
	v_and_b32_e32 v41, 0xffff0000, v24
	v_fma_f32 v4, v4, s48, v40
	v_fma_f32 v5, v5, s48, v41
	v_cvt_pk_bf16_f32 v6, v4, v5
	global_store_dword v2, v6, s[18:19]
	s_add_u32 s18, s18, 0x20000
	s_addc_u32 s19, s19, 0
	v_lshlrev_b32_e32 v40, 16, v25
	v_and_b32_e32 v41, 0xffff0000, v25
	v_fma_f32 v4, v4, s49, v40
	v_fma_f32 v5, v5, s49, v41
	v_cvt_pk_bf16_f32 v6, v4, v5
	global_store_dword v2, v6, s[18:19]
	s_add_u32 s18, s18, 0x20000
	s_addc_u32 s19, s19, 0
	v_lshlrev_b32_e32 v40, 16, v26
	v_and_b32_e32 v41, 0xffff0000, v26
	v_fma_f32 v4, v4, s50, v40
	v_fma_f32 v5, v5, s50, v41
	v_cvt_pk_bf16_f32 v6, v4, v5
	global_store_dword v2, v6, s[18:19]
	s_add_u32 s18, s18, 0x20000
	s_addc_u32 s19, s19, 0
	v_lshlrev_b32_e32 v40, 16, v27
	v_and_b32_e32 v41, 0xffff0000, v27
	v_fma_f32 v4, v4, s51, v40
	v_fma_f32 v5, v5, s51, v41
	v_cvt_pk_bf16_f32 v6, v4, v5
	global_store_dword v2, v6, s[18:19]
	s_add_u32 s18, s18, 0x20000
	s_addc_u32 s19, s19, 0
	v_lshlrev_b32_e32 v40, 16, v28
	v_and_b32_e32 v41, 0xffff0000, v28
	v_fma_f32 v4, v4, s52, v40
	v_fma_f32 v5, v5, s52, v41
	v_cvt_pk_bf16_f32 v6, v4, v5
	global_store_dword v2, v6, s[18:19]
	s_add_u32 s18, s18, 0x20000
	s_addc_u32 s19, s19, 0
	v_lshlrev_b32_e32 v40, 16, v29
	v_and_b32_e32 v41, 0xffff0000, v29
	v_fma_f32 v4, v4, s53, v40
	v_fma_f32 v5, v5, s53, v41
	v_cvt_pk_bf16_f32 v6, v4, v5
	global_store_dword v2, v6, s[18:19]
	s_add_u32 s18, s18, 0x20000
	s_addc_u32 s19, s19, 0
	v_lshlrev_b32_e32 v40, 16, v30
	v_and_b32_e32 v41, 0xffff0000, v30
	v_fma_f32 v4, v4, s54, v40
	v_fma_f32 v5, v5, s54, v41
	v_cvt_pk_bf16_f32 v6, v4, v5
	global_store_dword v2, v6, s[18:19]
	s_add_u32 s18, s18, 0x20000
	s_addc_u32 s19, s19, 0
	v_lshlrev_b32_e32 v40, 16, v31
	v_and_b32_e32 v41, 0xffff0000, v31
	v_fma_f32 v4, v4, s55, v40
	v_fma_f32 v5, v5, s55, v41
	global_load_dword v24, v2, s[16:17] nt
	s_add_u32 s16, s16, 0x20000
	s_addc_u32 s17, s17, 0
	global_load_dword v25, v2, s[16:17] nt
	s_add_u32 s16, s16, 0x20000
	s_addc_u32 s17, s17, 0
	global_load_dword v26, v2, s[16:17] nt
	s_add_u32 s16, s16, 0x20000
	s_addc_u32 s17, s17, 0
	global_load_dword v27, v2, s[16:17] nt
	s_add_u32 s16, s16, 0x20000
	s_addc_u32 s17, s17, 0
	global_load_dword v28, v2, s[16:17] nt
	s_add_u32 s16, s16, 0x20000
	s_addc_u32 s17, s17, 0
	global_load_dword v29, v2, s[16:17] nt
	s_add_u32 s16, s16, 0x20000
	s_addc_u32 s17, s17, 0
	global_load_dword v30, v2, s[16:17] nt
	s_add_u32 s16, s16, 0x20000
	s_addc_u32 s17, s17, 0
	global_load_dword v31, v2, s[16:17] nt
	s_add_u32 s16, s16, 0x20000
	s_addc_u32 s17, s17, 0
	s_load_dword s48, s[24:25], 0x0
	s_load_dword s49, s[24:25], 0x20
	s_load_dword s50, s[24:25], 0x40
	s_load_dword s51, s[24:25], 0x60
	s_load_dword s52, s[24:25], 0x80
	s_load_dword s53, s[24:25], 0xa0
	s_load_dword s54, s[24:25], 0xc0
	s_load_dword s55, s[24:25], 0xe0
	s_add_u32 s24, s24, 0x100
	s_addc_u32 s25, s25, 0
	s_waitcnt vmcnt(48) lgkmcnt(0)
	v_cvt_pk_bf16_f32 v6, v4, v5
	global_store_dword v2, v6, s[18:19]
	s_add_u32 s18, s18, 0x20000
	s_addc_u32 s19, s19, 0
	v_lshlrev_b32_e32 v40, 16, v32
	v_and_b32_e32 v41, 0xffff0000, v32
	v_fma_f32 v4, v4, s56, v40
	v_fma_f32 v5, v5, s56, v41
	v_cvt_pk_bf16_f32 v6, v4, v5
	global_store_dword v2, v6, s[18:19]
	s_add_u32 s18, s18, 0x20000
	s_addc_u32 s19, s19, 0
	v_lshlrev_b32_e32 v40, 16, v33
	v_and_b32_e32 v41, 0xffff0000, v33
	v_fma_f32 v4, v4, s57, v40
	v_fma_f32 v5, v5, s57, v41
	v_cvt_pk_bf16_f32 v6, v4, v5
	global_store_dword v2, v6, s[18:19]
	s_add_u32 s18, s18, 0x20000
	s_addc_u32 s19, s19, 0
	v_lshlrev_b32_e32 v40, 16, v34
	v_and_b32_e32 v41, 0xffff0000, v34
	v_fma_f32 v4, v4, s58, v40
	v_fma_f32 v5, v5, s58, v41
	v_cvt_pk_bf16_f32 v6, v4, v5
	global_store_dword v2, v6, s[18:19]
	s_add_u32 s18, s18, 0x20000
	s_addc_u32 s19, s19, 0
	v_lshlrev_b32_e32 v40, 16, v35
	v_and_b32_e32 v41, 0xffff0000, v35
	v_fma_f32 v4, v4, s59, v40
	v_fma_f32 v5, v5, s59, v41
	v_cvt_pk_bf16_f32 v6, v4, v5
	global_store_dword v2, v6, s[18:19]
	s_add_u32 s18, s18, 0x20000
	s_addc_u32 s19, s19, 0
	v_lshlrev_b32_e32 v40, 16, v36
	v_and_b32_e32 v41, 0xffff0000, v36
	v_fma_f32 v4, v4, s60, v40
	v_fma_f32 v5, v5, s60, v41
	v_cvt_pk_bf16_f32 v6, v4, v5
	global_store_dword v2, v6, s[18:19]
	s_add_u32 s18, s18, 0x20000
	s_addc_u32 s19, s19, 0
	v_lshlrev_b32_e32 v40, 16, v37
	v_and_b32_e32 v41, 0xffff0000, v37
	v_fma_f32 v4, v4, s61, v40
	v_fma_f32 v5, v5, s61, v41
	v_cvt_pk_bf16_f32 v6, v4, v5
	global_store_dword v2, v6, s[18:19]
	s_add_u32 s18, s18, 0x20000
	s_addc_u32 s19, s19, 0
	v_lshlrev_b32_e32 v40, 16, v38
	v_and_b32_e32 v41, 0xffff0000, v38
	v_fma_f32 v4, v4, s62, v40
	v_fma_f32 v5, v5, s62, v41
	v_cvt_pk_bf16_f32 v6, v4, v5
	global_store_dword v2, v6, s[18:19]
	s_add_u32 s18, s18, 0x20000
	s_addc_u32 s19, s19, 0
	v_lshlrev_b32_e32 v40, 16, v39
	v_and_b32_e32 v41, 0xffff0000, v39
	v_fma_f32 v4, v4, s63, v40
	v_fma_f32 v5, v5, s63, v41
	global_load_dword v32, v2, s[16:17] nt
	s_add_u32 s16, s16, 0x20000
	s_addc_u32 s17, s17, 0
	global_load_dword v33, v2, s[16:17] nt
	s_add_u32 s16, s16, 0x20000
	s_addc_u32 s17, s17, 0
	global_load_dword v34, v2, s[16:17] nt
	s_add_u32 s16, s16, 0x20000
	s_addc_u32 s17, s17, 0
	global_load_dword v35, v2, s[16:17] nt
	s_add_u32 s16, s16, 0x20000
	s_addc_u32 s17, s17, 0
	global_load_dword v36, v2, s[16:17] nt
	s_add_u32 s16, s16, 0x20000
	s_addc_u32 s17, s17, 0
	global_load_dword v37, v2, s[16:17] nt
	s_add_u32 s16, s16, 0x20000
	s_addc_u32 s17, s17, 0
	global_load_dword v38, v2, s[16:17] nt
	s_add_u32 s16, s16, 0x20000
	s_addc_u32 s17, s17, 0
	global_load_dword v39, v2, s[16:17] nt
	s_add_u32 s16, s16, 0x20000
	s_addc_u32 s17, s17, 0
	s_load_dword s56, s[24:25], 0x0
	s_load_dword s57, s[24:25], 0x20
	s_load_dword s58, s[24:25], 0x40
	s_load_dword s59, s[24:25], 0x60
	s_load_dword s60, s[24:25], 0x80
	s_load_dword s61, s[24:25], 0xa0
	s_load_dword s62, s[24:25], 0xc0
	s_load_dword s63, s[24:25], 0xe0
	s_add_u32 s24, s24, 0x100
	s_addc_u32 s25, s25, 0
	s_sub_u32 s22, s22, 1
	s_cmp_lg_u32 s22, 0
	s_cbranch_scc1 .Lp3_ssd_loop
	s_waitcnt vmcnt(48) lgkmcnt(0)
	v_cvt_pk_bf16_f32 v6, v4, v5
	global_store_dword v2, v6, s[18:19]
	s_add_u32 s18, s18, 0x20000
	s_addc_u32 s19, s19, 0
	v_lshlrev_b32_e32 v40, 16, v8
	v_and_b32_e32 v41, 0xffff0000, v8
	v_fma_f32 v4, v4, s32, v40
	v_fma_f32 v5, v5, s32, v41
	v_cvt_pk_bf16_f32 v6, v4, v5
	global_store_dword v2, v6, s[18:19]
	s_add_u32 s18, s18, 0x20000
	s_addc_u32 s19, s19, 0
	v_lshlrev_b32_e32 v40, 16, v9
	v_and_b32_e32 v41, 0xffff0000, v9
	v_fma_f32 v4, v4, s33, v40
	v_fma_f32 v5, v5, s33, v41
	v_cvt_pk_bf16_f32 v6, v4, v5
	global_store_dword v2, v6, s[18:19]
	s_add_u32 s18, s18, 0x20000
	s_addc_u32 s19, s19, 0
	v_lshlrev_b32_e32 v40, 16, v10
	v_and_b32_e32 v41, 0xffff0000, v10
	v_fma_f32 v4, v4, s34, v40
	v_fma_f32 v5, v5, s34, v41
	v_cvt_pk_bf16_f32 v6, v4, v5
	global_store_dword v2, v6, s[18:19]
	s_add_u32 s18, s18, 0x20000
	s_addc_u32 s19, s19, 0
	v_lshlrev_b32_e32 v40, 16, v11
	v_and_b32_e32 v41, 0xffff0000, v11
	v_fma_f32 v4, v4, s35, v40
	v_fma_f32 v5, v5, s35, v41
	v_cvt_pk_bf16_f32 v6, v4, v5
	global_store_dword v2, v6, s[18:19]
	s_add_u32 s18, s18, 0x20000
	s_addc_u32 s19, s19, 0
	v_lshlrev_b32_e32 v40, 16, v12
	v_and_b32_e32 v41, 0xffff0000, v12
	v_fma_f32 v4, v4, s36, v40
	v_fma_f32 v5, v5, s36, v41
	v_cvt_pk_bf16_f32 v6, v4, v5
	global_store_dword v2, v6, s[18:19]
	s_add_u32 s18, s18, 0x20000
	s_addc_u32 s19, s19, 0
	v_lshlrev_b32_e32 v40, 16, v13
	v_and_b32_e32 v41, 0xffff0000, v13
	v_fma_f32 v4, v4, s37, v40
	v_fma_f32 v5, v5, s37, v41
	v_cvt_pk_bf16_f32 v6, v4, v5
	global_store_dword v2, v6, s[18:19]
	s_add_u32 s18, s18, 0x20000
	s_addc_u32 s19, s19, 0
	v_lshlrev_b32_e32 v40, 16, v14
	v_and_b32_e32 v41, 0xffff0000, v14
	v_fma_f32 v4, v4, s38, v40
	v_fma_f32 v5, v5, s38, v41
	v_cvt_pk_bf16_f32 v6, v4, v5
	global_store_dword v2, v6, s[18:19]
	s_add_u32 s18, s18, 0x20000
	s_addc_u32 s19, s19, 0
	v_lshlrev_b32_e32 v40, 16, v15
	v_and_b32_e32 v41, 0xffff0000, v15
	v_fma_f32 v4, v4, s39, v40
	v_fma_f32 v5, v5, s39, v41
	s_waitcnt vmcnt(40) lgkmcnt(0)
	v_cvt_pk_bf16_f32 v6, v4, v5
	global_store_dword v2, v6, s[18:19]
	s_add_u32 s18, s18, 0x20000
	s_addc_u32 s19, s19, 0
	v_lshlrev_b32_e32 v40, 16, v16
	v_and_b32_e32 v41, 0xffff0000, v16
	v_fma_f32 v4, v4, s40, v40
	v_fma_f32 v5, v5, s40, v41
	v_cvt_pk_bf16_f32 v6, v4, v5
	global_store_dword v2, v6, s[18:19]
	s_add_u32 s18, s18, 0x20000
	s_addc_u32 s19, s19, 0
	v_lshlrev_b32_e32 v40, 16, v17
	v_and_b32_e32 v41, 0xffff0000, v17
	v_fma_f32 v4, v4, s41, v40
	v_fma_f32 v5, v5, s41, v41
	v_cvt_pk_bf16_f32 v6, v4, v5
	global_store_dword v2, v6, s[18:19]
	s_add_u32 s18, s18, 0x20000
	s_addc_u32 s19, s19, 0
	v_lshlrev_b32_e32 v40, 16, v18
	v_and_b32_e32 v41, 0xffff0000, v18
	v_fma_f32 v4, v4, s42, v40
	v_fma_f32 v5, v5, s42, v41
	v_cvt_pk_bf16_f32 v6, v4, v5
	global_store_dword v2, v6, s[18:19]
	s_add_u32 s18, s18, 0x20000
	s_addc_u32 s19, s19, 0
	v_lshlrev_b32_e32 v40, 16, v19
	v_and_b32_e32 v41, 0xffff0000, v19
	v_fma_f32 v4, v4, s43, v40
	v_fma_f32 v5, v5, s43, v41
	v_cvt_pk_bf16_f32 v6, v4, v5
	global_store_dword v2, v6, s[18:19]
	s_add_u32 s18, s18, 0x20000
	s_addc_u32 s19, s19, 0
	v_lshlrev_b32_e32 v40, 16, v20
	v_and_b32_e32 v41, 0xffff0000, v20
	v_fma_f32 v4, v4, s44, v40
	v_fma_f32 v5, v5, s44, v41
	v_cvt_pk_bf16_f32 v6, v4, v5
	global_store_dword v2, v6, s[18:19]
	s_add_u32 s18, s18, 0x20000
	s_addc_u32 s19, s19, 0
	v_lshlrev_b32_e32 v40, 16, v21
	v_and_b32_e32 v41, 0xffff0000, v21
	v_fma_f32 v4, v4, s45, v40
	v_fma_f32 v5, v5, s45, v41
	v_cvt_pk_bf16_f32 v6, v4, v5
	global_store_dword v2, v6, s[18:19]
	s_add_u32 s18, s18, 0x20000
	s_addc_u32 s19, s19, 0
	v_lshlrev_b32_e32 v40, 16, v22
	v_and_b32_e32 v41, 0xffff0000, v22
	v_fma_f32 v4, v4, s46, v40
	v_fma_f32 v5, v5, s46, v41
	v_cvt_pk_bf16_f32 v6, v4, v5
	global_store_dword v2, v6, s[18:19]
	s_add_u32 s18, s18, 0x20000
	s_addc_u32 s19, s19, 0
	v_lshlrev_b32_e32 v40, 16, v23
	v_and_b32_e32 v41, 0xffff0000, v23
	v_fma_f32 v4, v4, s47, v40
	v_fma_f32 v5, v5, s47, v41
	s_waitcnt vmcnt(32) lgkmcnt(0)
	v_cvt_pk_bf16_f32 v6, v4, v5
	global_store_dword v2, v6, s[18:19]
	s_add_u32 s18, s18, 0x20000
	s_addc_u32 s19, s19, 0
	v_lshlrev_b32_e32 v40, 16, v24
	v_and_b32_e32 v41, 0xffff0000, v24
	v_fma_f32 v4, v4, s48, v40
	v_fma_f32 v5, v5, s48, v41
	v_cvt_pk_bf16_f32 v6, v4, v5
	global_store_dword v2, v6, s[18:19]
	s_add_u32 s18, s18, 0x20000
	s_addc_u32 s19, s19, 0
	v_lshlrev_b32_e32 v40, 16, v25
	v_and_b32_e32 v41, 0xffff0000, v25
	v_fma_f32 v4, v4, s49, v40
	v_fma_f32 v5, v5, s49, v41
	v_cvt_pk_bf16_f32 v6, v4, v5
	global_store_dword v2, v6, s[18:19]
	s_add_u32 s18, s18, 0x20000
	s_addc_u32 s19, s19, 0
	v_lshlrev_b32_e32 v40, 16, v26
	v_and_b32_e32 v41, 0xffff0000, v26
	v_fma_f32 v4, v4, s50, v40
	v_fma_f32 v5, v5, s50, v41
	v_cvt_pk_bf16_f32 v6, v4, v5
	global_store_dword v2, v6, s[18:19]
	s_add_u32 s18, s18, 0x20000
	s_addc_u32 s19, s19, 0
	v_lshlrev_b32_e32 v40, 16, v27
	v_and_b32_e32 v41, 0xffff0000, v27
	v_fma_f32 v4, v4, s51, v40
	v_fma_f32 v5, v5, s51, v41
	v_cvt_pk_bf16_f32 v6, v4, v5
	global_store_dword v2, v6, s[18:19]
	s_add_u32 s18, s18, 0x20000
	s_addc_u32 s19, s19, 0
	v_lshlrev_b32_e32 v40, 16, v28
	v_and_b32_e32 v41, 0xffff0000, v28
	v_fma_f32 v4, v4, s52, v40
	v_fma_f32 v5, v5, s52, v41
	v_cvt_pk_bf16_f32 v6, v4, v5
	global_store_dword v2, v6, s[18:19]
	s_add_u32 s18, s18, 0x20000
	s_addc_u32 s19, s19, 0
	v_lshlrev_b32_e32 v40, 16, v29
	v_and_b32_e32 v41, 0xffff0000, v29
	v_fma_f32 v4, v4, s53, v40
	v_fma_f32 v5, v5, s53, v41
	v_cvt_pk_bf16_f32 v6, v4, v5
	global_store_dword v2, v6, s[18:19]
	s_add_u32 s18, s18, 0x20000
	s_addc_u32 s19, s19, 0
	v_lshlrev_b32_e32 v40, 16, v30
	v_and_b32_e32 v41, 0xffff0000, v30
	v_fma_f32 v4, v4, s54, v40
	v_fma_f32 v5, v5, s54, v41
	v_cvt_pk_bf16_f32 v6, v4, v5
	global_store_dword v2, v6, s[18:19]
	s_add_u32 s18, s18, 0x20000
	s_addc_u32 s19, s19, 0
	v_lshlrev_b32_e32 v40, 16, v31
	v_and_b32_e32 v41, 0xffff0000, v31
	v_fma_f32 v4, v4, s55, v40
	v_fma_f32 v5, v5, s55, v41
	s_waitcnt vmcnt(24) lgkmcnt(0)
	v_cvt_pk_bf16_f32 v6, v4, v5
	global_store_dword v2, v6, s[18:19]
	s_add_u32 s18, s18, 0x20000
	s_addc_u32 s19, s19, 0
	v_lshlrev_b32_e32 v40, 16, v32
	v_and_b32_e32 v41, 0xffff0000, v32
	v_fma_f32 v4, v4, s56, v40
	v_fma_f32 v5, v5, s56, v41
	v_cvt_pk_bf16_f32 v6, v4, v5
	global_store_dword v2, v6, s[18:19]
	s_add_u32 s18, s18, 0x20000
	s_addc_u32 s19, s19, 0
	v_lshlrev_b32_e32 v40, 16, v33
	v_and_b32_e32 v41, 0xffff0000, v33
	v_fma_f32 v4, v4, s57, v40
	v_fma_f32 v5, v5, s57, v41
	v_cvt_pk_bf16_f32 v6, v4, v5
	global_store_dword v2, v6, s[18:19]
	s_add_u32 s18, s18, 0x20000
	s_addc_u32 s19, s19, 0
	v_lshlrev_b32_e32 v40, 16, v34
	v_and_b32_e32 v41, 0xffff0000, v34
	v_fma_f32 v4, v4, s58, v40
	v_fma_f32 v5, v5, s58, v41
	v_cvt_pk_bf16_f32 v6, v4, v5
	global_store_dword v2, v6, s[18:19]
	s_add_u32 s18, s18, 0x20000
	s_addc_u32 s19, s19, 0
	v_lshlrev_b32_e32 v40, 16, v35
	v_and_b32_e32 v41, 0xffff0000, v35
	v_fma_f32 v4, v4, s59, v40
	v_fma_f32 v5, v5, s59, v41
	v_cvt_pk_bf16_f32 v6, v4, v5
	global_store_dword v2, v6, s[18:19]
	s_add_u32 s18, s18, 0x20000
	s_addc_u32 s19, s19, 0
	v_lshlrev_b32_e32 v40, 16, v36
	v_and_b32_e32 v41, 0xffff0000, v36
	v_fma_f32 v4, v4, s60, v40
	v_fma_f32 v5, v5, s60, v41
	v_cvt_pk_bf16_f32 v6, v4, v5
	global_store_dword v2, v6, s[18:19]
	s_add_u32 s18, s18, 0x20000
	s_addc_u32 s19, s19, 0
	v_lshlrev_b32_e32 v40, 16, v37
	v_and_b32_e32 v41, 0xffff0000, v37
	v_fma_f32 v4, v4, s61, v40
	v_fma_f32 v5, v5, s61, v41
	v_cvt_pk_bf16_f32 v6, v4, v5
	global_store_dword v2, v6, s[18:19]
	s_add_u32 s18, s18, 0x20000
	s_addc_u32 s19, s19, 0
	v_lshlrev_b32_e32 v40, 16, v38
	v_and_b32_e32 v41, 0xffff0000, v38
	v_fma_f32 v4, v4, s62, v40
	v_fma_f32 v5, v5, s62, v41
	v_cvt_pk_bf16_f32 v6, v4, v5
	global_store_dword v2, v6, s[18:19]
	s_add_u32 s18, s18, 0x20000
	s_addc_u32 s19, s19, 0
	v_lshlrev_b32_e32 v40, 16, v39
	v_and_b32_e32 v41, 0xffff0000, v39
	v_fma_f32 v4, v4, s63, v40
	v_fma_f32 v5, v5, s63, v41
